# GEMM epilogues staggered (template ALIGN_EPI=false mode): align barrier only on the last unit, restore barrier removed, so the leading half epilogue overlaps the trailing half last MFMA block
# baseline (speedup 1.0000x reference)
; #define PG8_STAGE(bufoff, gbase, voff) do { _Pragma("unroll") for (int _i = 0; _i < 2; ++_i) \
;         __builtin_amdgcn_global_load_lds((const unsigned*)((const char*)(gbase) + (voff)[_i]), (PG8_LAS unsigned*)(lds + (bufoff) + ldsw + _i * 8192), 16, 0, 0); } while (0)
; #define PG8_LDA(dst, b, h) do { _Pragma("unroll") for (int m = 0; m < 4; ++m) _Pragma("unroll") for (int k = 0; k < 2; ++k) dst[m][k] = *(const PG8_LAS bf16x8*)(lds + PG8_SA(b, h) + aoff + m * 2048 + k * 1024); } while (0)
; #define PG8_LDB(dst, b, h) do { _Pragma("unroll") for (int n = 0; n < 2; ++n) _Pragma("unroll") for (int k = 0; k < 2; ++k) dst[n][k] = *(const PG8_LAS bf16x8*)(lds + PG8_SB(b, h) + boff + n * 2048 + k * 1024); } while (0)
; #define PG8_MMA(ai, bj, At, Bt) do { __builtin_amdgcn_s_setprio(1); _Pragma("unroll") for (int m = 0; m < 4; ++m) _Pragma("unroll") for (int n = 0; n < 2; ++n) _Pragma("unroll") for (int k = 0; k < 2; ++k) \
;         acc[ai][bj][m][n] = __builtin_amdgcn_mfma_f32_16x16x32_bf16(Bt[n][k], At[m][k], acc[ai][bj][m][n], 0, 0, 0); __builtin_amdgcn_s_setprio(0); } while (0)
; #define PG8_WAIT_V(n) asm volatile("s_waitcnt vmcnt(" #n ")" ::: "memory")
; #define PG8_WAIT_L(n) asm volatile("s_waitcnt lgkmcnt(" #n ")" ::: "memory")
; #define PG8_BAR __builtin_amdgcn_s_barrier()
; #define PG8_SCHED __builtin_amdgcn_sched_barrier(0)
; template <class Epi, class Sched, bool ALIGN_EPI = false, bool SP2 = false>
; __device__ __forceinline__ void gemm_phase(PG8_LAS unsigned char* lds, const Gemm g, const Sched& S, const Epi& E) {
;     ...
;             PG8_LDB(B0, 0, 0); PG8_LDB(B1, 0, 1); PG8_SCHED; PG8_LDA(At, 0, 0); PG8_STAGE(PG8_SA(1, 1), a1 + hstep, voffA);
;             PG8_WAIT_V(8); PG8_WAIT_L(0); PG8_BAR; PG8_MMA(0, 0, At, B0); PG8_MMA(0, 1, At, B1); PG8_BAR; PG8_SCHED;
;             PG8_LDA(At, 0, 1); PG8_STAGE(PG8_SB(0, 0), b2, voffB); PG8_STAGE(PG8_SB(0, 1), b2 + hstep, voffB); PG8_STAGE(PG8_SA(0, 0), a2, voffA);
;             PG8_WAIT_V(8); PG8_WAIT_L(0); PG8_BAR; PG8_MMA(1, 0, At, B0); PG8_MMA(1, 1, At, B1); PG8_BAR; PG8_SCHED;
.LBB0_95:
	s_add_u32 s2, s50, 0xfff80080
	s_addc_u32 s3, s51, -1
	s_add_i32 s20, 0, 0x10000
	s_cmp_eq_u32 s67, 28
	s_cselect_b32 s53, s45, s3
	s_cselect_b32 s52, s61, s2
	s_cselect_b32 s25, s43, s66
	s_cselect_b32 s24, s64, s65
	s_add_i32 s33, 0, 0x14000
	v_add_u32_e32 v126, s20, v163
	v_add_u32_e32 v250, s20, v249
	v_add_u32_e32 v160, s33, v163
	v_add_u32_e32 v251, s33, v249
	ds_read_b128 v[114:117], v126
	ds_read_b128 v[118:121], v250
	ds_read_b128 v[122:125], v126 offset:2048
	ds_read_b128 v[126:129], v250 offset:2048
	ds_read_b128 v[156:159], v160
	ds_read_b128 v[166:169], v251
	ds_read_b128 v[170:173], v160 offset:2048
	ds_read_b128 v[174:177], v251 offset:2048
	s_add_i32 m0, s7, 0xc000
	ds_read_b128 v[186:189], v165
	ds_read_b128 v[190:193], v248
	ds_read_b128 v[194:197], v165 offset:2048
	ds_read_b128 v[198:201], v248 offset:2048
	ds_read_b128 v[202:205], v165 offset:4096
	ds_read_b128 v[206:209], v248 offset:4096
	ds_read_b128 v[210:213], v165 offset:6144
	ds_read_b128 v[214:217], v248 offset:6144
	global_load_lds_dwordx4 v154, s[50:51]
	s_add_i32 m0, s7, 0xe000
	s_nop 0
	global_load_lds_dwordx4 v152, s[50:51]
	s_waitcnt vmcnt(8)
	s_waitcnt lgkmcnt(0)
	s_barrier
	s_setprio 1
	s_waitcnt lgkmcnt(0)
	v_mfma_f32_16x16x32_bf16 v[142:145], v[114:117], v[186:189], v[142:145]
	v_mfma_f32_16x16x32_bf16 v[138:141], v[122:125], v[186:189], v[138:141]
	v_mfma_f32_16x16x32_bf16 v[110:113], v[114:117], v[194:197], v[110:113]
	v_mfma_f32_16x16x32_bf16 v[106:109], v[122:125], v[194:197], v[106:109]
	v_mfma_f32_16x16x32_bf16 v[94:97], v[114:117], v[202:205], v[94:97]
	v_mfma_f32_16x16x32_bf16 v[90:93], v[122:125], v[202:205], v[90:93]
	v_mfma_f32_16x16x32_bf16 v[86:89], v[114:117], v[210:213], v[86:89]
	v_mfma_f32_16x16x32_bf16 v[78:81], v[122:125], v[210:213], v[78:81]
	v_mfma_f32_16x16x32_bf16 v[142:145], v[118:121], v[190:193], v[142:145]
	v_mfma_f32_16x16x32_bf16 v[138:141], v[126:129], v[190:193], v[138:141]
	v_mfma_f32_16x16x32_bf16 v[110:113], v[118:121], v[198:201], v[110:113]
	v_mfma_f32_16x16x32_bf16 v[106:109], v[126:129], v[198:201], v[106:109]
	v_mfma_f32_16x16x32_bf16 v[94:97], v[118:121], v[206:209], v[94:97]
	v_mfma_f32_16x16x32_bf16 v[90:93], v[126:129], v[206:209], v[90:93]
	v_mfma_f32_16x16x32_bf16 v[86:89], v[118:121], v[214:217], v[86:89]
	v_mfma_f32_16x16x32_bf16 v[78:81], v[126:129], v[214:217], v[78:81]
	s_setprio 0
	s_setprio 1
	v_mfma_f32_16x16x32_bf16 v[134:137], v[156:159], v[186:189], v[134:137]
	v_mfma_f32_16x16x32_bf16 v[130:133], v[170:173], v[186:189], v[130:133]
	v_mfma_f32_16x16x32_bf16 v[102:105], v[156:159], v[194:197], v[102:105]
	v_mfma_f32_16x16x32_bf16 v[98:101], v[170:173], v[194:197], v[98:101]
	v_mfma_f32_16x16x32_bf16 v[82:85], v[156:159], v[202:205], v[82:85]
	v_mfma_f32_16x16x32_bf16 v[74:77], v[170:173], v[202:205], v[74:77]
	v_mfma_f32_16x16x32_bf16 v[70:73], v[156:159], v[210:213], v[70:73]
	v_mfma_f32_16x16x32_bf16 v[66:69], v[170:173], v[210:213], v[66:69]
	v_mfma_f32_16x16x32_bf16 v[134:137], v[166:169], v[190:193], v[134:137]
	v_mfma_f32_16x16x32_bf16 v[130:133], v[174:177], v[190:193], v[130:133]
	v_mfma_f32_16x16x32_bf16 v[102:105], v[166:169], v[198:201], v[102:105]
	v_mfma_f32_16x16x32_bf16 v[98:101], v[174:177], v[198:201], v[98:101]
	v_mfma_f32_16x16x32_bf16 v[82:85], v[166:169], v[206:209], v[82:85]
	v_mfma_f32_16x16x32_bf16 v[74:77], v[174:177], v[206:209], v[74:77]
	v_mfma_f32_16x16x32_bf16 v[70:73], v[166:169], v[214:217], v[70:73]
	v_mfma_f32_16x16x32_bf16 v[66:69], v[174:177], v[214:217], v[66:69]
	s_setprio 0
	s_barrier
	s_add_i32 s2, s20, s6
	s_mov_b32 m0, s2
	ds_read_b128 v[186:189], v165 offset:16384
	ds_read_b128 v[190:193], v248 offset:16384
	ds_read_b128 v[194:197], v165 offset:18432
	ds_read_b128 v[198:201], v248 offset:18432
	ds_read_b128 v[202:205], v165 offset:20480
	ds_read_b128 v[206:209], v248 offset:20480
	ds_read_b128 v[210:213], v165 offset:22528
	ds_read_b128 v[214:217], v248 offset:22528
	global_load_lds_dwordx4 v0, s[24:25]
	s_add_i32 m0, s2, 0x2000
	s_add_u32 s2, s24, 0x80000
	s_addc_u32 s3, s25, 0
	s_add_i32 s20, s33, s6
	global_load_lds_dwordx4 v146, s[24:25]
	s_mov_b32 m0, s20
	s_nop 0
	global_load_lds_dwordx4 v0, s[2:3]
	s_add_i32 m0, s20, 0x2000
	s_nop 0
	global_load_lds_dwordx4 v146, s[2:3]
	s_mov_b32 m0, s7
	s_nop 0
	global_load_lds_dwordx4 v150, s[52:53]
	s_mov_b32 m0, s8
	s_nop 0
	global_load_lds_dwordx4 v148, s[52:53]
	s_waitcnt vmcnt(8)
	s_waitcnt lgkmcnt(0)
	s_barrier
	s_setprio 1
	s_waitcnt lgkmcnt(0)
	v_mfma_f32_16x16x32_bf16 v[62:65], v[114:117], v[186:189], v[62:65]
	v_mfma_f32_16x16x32_bf16 v[58:61], v[122:125], v[186:189], v[58:61]
	v_mfma_f32_16x16x32_bf16 v[54:57], v[114:117], v[194:197], v[54:57]
	v_mfma_f32_16x16x32_bf16 v[50:53], v[122:125], v[194:197], v[50:53]
	v_mfma_f32_16x16x32_bf16 v[38:41], v[114:117], v[202:205], v[38:41]
	v_mfma_f32_16x16x32_bf16 v[34:37], v[122:125], v[202:205], v[34:37]
	v_mfma_f32_16x16x32_bf16 v[22:25], v[114:117], v[210:213], v[22:25]
	v_mfma_f32_16x16x32_bf16 v[18:21], v[122:125], v[210:213], v[18:21]
	v_mfma_f32_16x16x32_bf16 v[62:65], v[118:121], v[190:193], v[62:65]
	v_mfma_f32_16x16x32_bf16 v[58:61], v[126:129], v[190:193], v[58:61]
	v_mfma_f32_16x16x32_bf16 v[54:57], v[118:121], v[198:201], v[54:57]
	v_mfma_f32_16x16x32_bf16 v[50:53], v[126:129], v[198:201], v[50:53]
	v_mfma_f32_16x16x32_bf16 v[38:41], v[118:121], v[206:209], v[38:41]
	v_mfma_f32_16x16x32_bf16 v[34:37], v[126:129], v[206:209], v[34:37]
	v_mfma_f32_16x16x32_bf16 v[22:25], v[118:121], v[214:217], v[22:25]
	v_mfma_f32_16x16x32_bf16 v[18:21], v[126:129], v[214:217], v[18:21]
	s_setprio 0
	s_setprio 1
	v_mfma_f32_16x16x32_bf16 v[46:49], v[156:159], v[186:189], v[46:49]
	v_mfma_f32_16x16x32_bf16 v[42:45], v[170:173], v[186:189], v[42:45]
	v_mfma_f32_16x16x32_bf16 v[30:33], v[156:159], v[194:197], v[30:33]
	v_mfma_f32_16x16x32_bf16 v[26:29], v[170:173], v[194:197], v[26:29]
	v_mfma_f32_16x16x32_bf16 v[14:17], v[156:159], v[202:205], v[14:17]
	v_mfma_f32_16x16x32_bf16 v[10:13], v[170:173], v[202:205], v[10:13]
	v_mfma_f32_16x16x32_bf16 v[6:9], v[156:159], v[210:213], v[6:9]
	v_mfma_f32_16x16x32_bf16 v[2:5], v[170:173], v[210:213], v[2:5]
	v_mfma_f32_16x16x32_bf16 v[46:49], v[166:169], v[190:193], v[46:49]
	v_mfma_f32_16x16x32_bf16 v[42:45], v[174:177], v[190:193], v[42:45]
	v_mfma_f32_16x16x32_bf16 v[30:33], v[166:169], v[198:201], v[30:33]
	v_mfma_f32_16x16x32_bf16 v[26:29], v[174:177], v[198:201], v[26:29]
	v_mfma_f32_16x16x32_bf16 v[14:17], v[166:169], v[206:209], v[14:17]
	v_mfma_f32_16x16x32_bf16 v[10:13], v[174:177], v[206:209], v[10:13]
	v_mfma_f32_16x16x32_bf16 v[6:9], v[166:169], v[214:217], v[6:9]
	v_mfma_f32_16x16x32_bf16 v[2:5], v[174:177], v[214:217], v[2:5]
	s_setprio 0
	s_barrier
; #define PG8_STAGE(bufoff, gbase, voff) do { _Pragma("unroll") for (int _i = 0; _i < 2; ++_i) \
;         __builtin_amdgcn_global_load_lds((const unsigned*)((const char*)(gbase) + (voff)[_i]), (PG8_LAS unsigned*)(lds + (bufoff) + ldsw + _i * 8192), 16, 0, 0); } while (0)
; #define PG8_LDA(dst, b, h) do { _Pragma("unroll") for (int m = 0; m < 4; ++m) _Pragma("unroll") for (int k = 0; k < 2; ++k) dst[m][k] = *(const PG8_LAS bf16x8*)(lds + PG8_SA(b, h) + aoff + m * 2048 + k * 1024); } while (0)
; #define PG8_LDB(dst, b, h) do { _Pragma("unroll") for (int n = 0; n < 2; ++n) _Pragma("unroll") for (int k = 0; k < 2; ++k) dst[n][k] = *(const PG8_LAS bf16x8*)(lds + PG8_SB(b, h) + boff + n * 2048 + k * 1024); } while (0)
; #define PG8_MMA(ai, bj, At, Bt) do { __builtin_amdgcn_s_setprio(1); _Pragma("unroll") for (int m = 0; m < 4; ++m) _Pragma("unroll") for (int n = 0; n < 2; ++n) _Pragma("unroll") for (int k = 0; k < 2; ++k) \
;         acc[ai][bj][m][n] = __builtin_amdgcn_mfma_f32_16x16x32_bf16(Bt[n][k], At[m][k], acc[ai][bj][m][n], 0, 0, 0); __builtin_amdgcn_s_setprio(0); } while (0)
; #define PG8_WAIT_V(n) asm volatile("s_waitcnt vmcnt(" #n ")" ::: "memory")
; #define PG8_WAIT_L(n) asm volatile("s_waitcnt lgkmcnt(" #n ")" ::: "memory")
; #define PG8_BAR __builtin_amdgcn_s_barrier()
; #define PG8_SCHED __builtin_amdgcn_sched_barrier(0)
; template <class Epi, class Sched, bool ALIGN_EPI = false, bool SP2 = false>
; __device__ __forceinline__ void gemm_phase(PG8_LAS unsigned char* lds, const Gemm g, const Sched& S, const Epi& E) {
;     ...
;             PG8_LDB(B0, 1, 0); PG8_LDB(B1, 1, 1); PG8_SCHED; PG8_LDA(At, 1, 0); PG8_STAGE(PG8_SA(0, 1), a2 + hstep, voffA);
;             PG8_WAIT_V(8); PG8_WAIT_L(0); PG8_BAR; PG8_MMA(0, 0, At, B0); PG8_MMA(0, 1, At, B1); PG8_BAR; PG8_SCHED;
;             PG8_LDA(At, 1, 1); PG8_STAGE(PG8_SB(1, 0), b3, voffB); PG8_STAGE(PG8_SB(1, 1), b3 + hstep, voffB); PG8_STAGE(PG8_SA(1, 0), a3, voffA);
;             PG8_WAIT_V(8); PG8_WAIT_L(0); PG8_BAR; PG8_MMA(1, 0, At, B0); PG8_MMA(1, 1, At, B1); PG8_BAR; PG8_SCHED;
;     ...
;         if constexpr (ALIGN_EPI) { if (wr == 0) PG8_BAR; }
	s_add_i32 s20, 0, 0x18000
	s_add_i32 s33, 0, 0x1c000
	v_add_u32_e32 v126, s20, v163
	v_add_u32_e32 v250, s20, v249
	v_add_u32_e32 v174, s33, v163
	v_add_u32_e32 v251, s33, v249
	ds_read_b128 v[114:117], v126
	ds_read_b128 v[118:121], v250
	ds_read_b128 v[122:125], v126 offset:2048
	ds_read_b128 v[126:129], v250 offset:2048
	ds_read_b128 v[156:159], v174
	ds_read_b128 v[166:169], v251
	ds_read_b128 v[170:173], v174 offset:2048
	ds_read_b128 v[174:177], v251 offset:2048
	s_add_u32 s2, s52, 0x80000
	s_addc_u32 s3, s53, 0
	s_mov_b32 m0, s9
	ds_read_b128 v[186:189], v165 offset:32768
	ds_read_b128 v[190:193], v248 offset:32768
	ds_read_b128 v[194:197], v165 offset:34816
	ds_read_b128 v[198:201], v248 offset:34816
	ds_read_b128 v[202:205], v165 offset:36864
	ds_read_b128 v[206:209], v248 offset:36864
	ds_read_b128 v[210:213], v165 offset:38912
	ds_read_b128 v[214:217], v248 offset:38912
	global_load_lds_dwordx4 v150, s[2:3]
	s_mov_b32 m0, s30
	s_nop 0
	global_load_lds_dwordx4 v148, s[2:3]
	s_waitcnt vmcnt(8)
	s_waitcnt lgkmcnt(0)
	s_barrier
	s_setprio 1
	s_waitcnt lgkmcnt(0)
	v_mfma_f32_16x16x32_bf16 v[142:145], v[114:117], v[186:189], v[142:145]
	v_mfma_f32_16x16x32_bf16 v[138:141], v[122:125], v[186:189], v[138:141]
	v_mfma_f32_16x16x32_bf16 v[110:113], v[114:117], v[194:197], v[110:113]
	v_mfma_f32_16x16x32_bf16 v[106:109], v[122:125], v[194:197], v[106:109]
	v_mfma_f32_16x16x32_bf16 v[94:97], v[114:117], v[202:205], v[94:97]
	v_mfma_f32_16x16x32_bf16 v[90:93], v[122:125], v[202:205], v[90:93]
	v_mfma_f32_16x16x32_bf16 v[86:89], v[114:117], v[210:213], v[86:89]
	v_mfma_f32_16x16x32_bf16 v[78:81], v[122:125], v[210:213], v[78:81]
	v_mfma_f32_16x16x32_bf16 v[142:145], v[118:121], v[190:193], v[142:145]
	v_mfma_f32_16x16x32_bf16 v[138:141], v[126:129], v[190:193], v[138:141]
	v_mfma_f32_16x16x32_bf16 v[110:113], v[118:121], v[198:201], v[110:113]
	v_mfma_f32_16x16x32_bf16 v[106:109], v[126:129], v[198:201], v[106:109]
	v_mfma_f32_16x16x32_bf16 v[94:97], v[118:121], v[206:209], v[94:97]
	v_mfma_f32_16x16x32_bf16 v[90:93], v[126:129], v[206:209], v[90:93]
	v_mfma_f32_16x16x32_bf16 v[86:89], v[118:121], v[214:217], v[86:89]
	v_mfma_f32_16x16x32_bf16 v[78:81], v[126:129], v[214:217], v[78:81]
	s_setprio 0
	s_setprio 1
	v_mfma_f32_16x16x32_bf16 v[134:137], v[156:159], v[186:189], v[134:137]
	v_mfma_f32_16x16x32_bf16 v[130:133], v[170:173], v[186:189], v[130:133]
	v_mfma_f32_16x16x32_bf16 v[102:105], v[156:159], v[194:197], v[102:105]
	v_mfma_f32_16x16x32_bf16 v[98:101], v[170:173], v[194:197], v[98:101]
	v_mfma_f32_16x16x32_bf16 v[82:85], v[156:159], v[202:205], v[82:85]
	v_mfma_f32_16x16x32_bf16 v[74:77], v[170:173], v[202:205], v[74:77]
	v_mfma_f32_16x16x32_bf16 v[70:73], v[156:159], v[210:213], v[70:73]
	v_mfma_f32_16x16x32_bf16 v[66:69], v[170:173], v[210:213], v[66:69]
	v_mfma_f32_16x16x32_bf16 v[134:137], v[166:169], v[190:193], v[134:137]
	v_mfma_f32_16x16x32_bf16 v[130:133], v[174:177], v[190:193], v[130:133]
	v_mfma_f32_16x16x32_bf16 v[102:105], v[166:169], v[198:201], v[102:105]
	v_mfma_f32_16x16x32_bf16 v[98:101], v[174:177], v[198:201], v[98:101]
	v_mfma_f32_16x16x32_bf16 v[82:85], v[166:169], v[206:209], v[82:85]
	v_mfma_f32_16x16x32_bf16 v[74:77], v[174:177], v[206:209], v[74:77]
	v_mfma_f32_16x16x32_bf16 v[70:73], v[166:169], v[214:217], v[70:73]
	v_mfma_f32_16x16x32_bf16 v[66:69], v[174:177], v[214:217], v[66:69]
	s_setprio 0
	s_barrier
	s_add_i32 s2, s20, s6
	s_add_i32 m0, s2, 0xffffff80
	ds_read_b128 v[186:189], v165 offset:49152
	ds_read_b128 v[190:193], v248 offset:49152
	ds_read_b128 v[194:197], v165 offset:51200
	ds_read_b128 v[198:201], v248 offset:51200
	ds_read_b128 v[202:205], v165 offset:53248
	ds_read_b128 v[206:209], v248 offset:53248
	ds_read_b128 v[210:213], v165 offset:55296
	ds_read_b128 v[214:217], v248 offset:55296
	global_load_lds_dwordx4 v0, s[24:25] offset:128
	s_add_i32 m0, s2, 0x1f80
	s_add_u32 s2, s24, 0x80080
	s_addc_u32 s3, s25, 0
	s_add_i32 s20, s33, s6
	global_load_lds_dwordx4 v146, s[24:25] offset:128
	s_mov_b32 m0, s20
	s_nop 0
	global_load_lds_dwordx4 v0, s[2:3]
	s_add_i32 m0, s20, 0x2000
	s_nop 0
	global_load_lds_dwordx4 v146, s[2:3]
	s_add_i32 m0, s56, 0xffffff80
	s_nop 0
	global_load_lds_dwordx4 v150, s[52:53] offset:128
	s_add_i32 m0, s57, 0xffffff80
	s_nop 0
	global_load_lds_dwordx4 v148, s[52:53] offset:128
	s_waitcnt vmcnt(8)
	s_waitcnt lgkmcnt(0)
	s_barrier
	s_setprio 1
	s_waitcnt lgkmcnt(0)
	v_mfma_f32_16x16x32_bf16 v[62:65], v[114:117], v[186:189], v[62:65]
	v_mfma_f32_16x16x32_bf16 v[58:61], v[122:125], v[186:189], v[58:61]
	v_mfma_f32_16x16x32_bf16 v[54:57], v[114:117], v[194:197], v[54:57]
	v_mfma_f32_16x16x32_bf16 v[50:53], v[122:125], v[194:197], v[50:53]
	v_mfma_f32_16x16x32_bf16 v[38:41], v[114:117], v[202:205], v[38:41]
	v_mfma_f32_16x16x32_bf16 v[34:37], v[122:125], v[202:205], v[34:37]
	v_mfma_f32_16x16x32_bf16 v[22:25], v[114:117], v[210:213], v[22:25]
	v_mfma_f32_16x16x32_bf16 v[18:21], v[122:125], v[210:213], v[18:21]
	v_mfma_f32_16x16x32_bf16 v[62:65], v[118:121], v[190:193], v[62:65]
	v_mfma_f32_16x16x32_bf16 v[58:61], v[126:129], v[190:193], v[58:61]
	v_mfma_f32_16x16x32_bf16 v[54:57], v[118:121], v[198:201], v[54:57]
	v_mfma_f32_16x16x32_bf16 v[50:53], v[126:129], v[198:201], v[50:53]
	v_mfma_f32_16x16x32_bf16 v[38:41], v[118:121], v[206:209], v[38:41]
	v_mfma_f32_16x16x32_bf16 v[34:37], v[126:129], v[206:209], v[34:37]
	v_mfma_f32_16x16x32_bf16 v[22:25], v[118:121], v[214:217], v[22:25]
	v_mfma_f32_16x16x32_bf16 v[18:21], v[126:129], v[214:217], v[18:21]
	s_setprio 0
	s_setprio 1
	v_mfma_f32_16x16x32_bf16 v[46:49], v[156:159], v[186:189], v[46:49]
	v_mfma_f32_16x16x32_bf16 v[42:45], v[170:173], v[186:189], v[42:45]
	v_mfma_f32_16x16x32_bf16 v[30:33], v[156:159], v[194:197], v[30:33]
	v_mfma_f32_16x16x32_bf16 v[26:29], v[170:173], v[194:197], v[26:29]
	v_mfma_f32_16x16x32_bf16 v[14:17], v[156:159], v[202:205], v[14:17]
	v_mfma_f32_16x16x32_bf16 v[10:13], v[170:173], v[202:205], v[10:13]
	v_mfma_f32_16x16x32_bf16 v[6:9], v[156:159], v[210:213], v[6:9]
	v_mfma_f32_16x16x32_bf16 v[2:5], v[170:173], v[210:213], v[2:5]
	v_mfma_f32_16x16x32_bf16 v[46:49], v[166:169], v[190:193], v[46:49]
	v_mfma_f32_16x16x32_bf16 v[42:45], v[174:177], v[190:193], v[42:45]
	v_mfma_f32_16x16x32_bf16 v[30:33], v[166:169], v[198:201], v[30:33]
	v_mfma_f32_16x16x32_bf16 v[26:29], v[174:177], v[198:201], v[26:29]
	v_mfma_f32_16x16x32_bf16 v[14:17], v[166:169], v[206:209], v[14:17]
	v_mfma_f32_16x16x32_bf16 v[10:13], v[174:177], v[206:209], v[10:13]
	v_mfma_f32_16x16x32_bf16 v[6:9], v[166:169], v[214:217], v[6:9]
	v_mfma_f32_16x16x32_bf16 v[2:5], v[174:177], v[214:217], v[2:5]
	s_setprio 0
	s_barrier
	s_add_i32 s67, s67, 2
	s_add_u32 s65, s65, 0x100
	s_addc_u32 s66, s66, 0
	s_add_u32 s50, s50, 0x100
	s_addc_u32 s51, s51, 0
	s_cmp_gt_u32 s67, 29
	s_cbranch_scc0 .LBB0_95
	s_and_b64 vcc, exec, s[26:27]
	s_cbranch_vccz .LBB0_98
	s_and_b64 vcc, exec, s[40:41]
	s_cbranch_vccnz .LBB0_98
	s_barrier
; __device__ __forceinline__ void st8(bf16_t* p, const float (&v)[8]) { u32x4 w; w.x = pk2(v[0], v[1]); w.y = pk2(v[2], v[3]); w.z = pk2(v[4], v[5]); w.w = pk2(v[6], v[7]); *(u32x4*)p = w; }
;     __device__ __forceinline__ void operator()(const f32x4 (&acc)[2][2][4][2], const Unit& u, int wr, int wc, int fr, int fq) const {
;         if (!dl) return;
;         const int row0 = u.pm * 256 + wr * 64 + fr, col0 = u.pn * 256 + wc * 32 + 8 * fq;
;         const float* gp = gate + (size_t)(u.pm >> 4) * 6144 + col0;
;         f32x4 g[2][2];
; #pragma unroll
;         for (int bj = 0; bj < 2; ++bj)
; #pragma unroll
;             for (int n = 0; n < 2; ++n) g[bj][n] = *(const f32x4*)(gp + bj * 128 + n * 4);
; #pragma unroll
;         for (int ai = 0; ai < 2; ++ai)
; #pragma unroll
;             for (int m = 0; m < 4; ++m) { bf16_t* rp = dl + (size_t)(row0 + ai * 128 + m * 16) * DM + col0;
; #pragma unroll
;                 for (int bj = 0; bj < 2; ++bj) { float o[8];
; #pragma unroll
;                     for (int j = 0; j < 4; ++j) { o[j] = g[bj][0][j] * acc[ai][bj][m][0][j]; o[4 + j] = g[bj][1][j] * acc[ai][bj][m][1][j]; }
;                     st8(rp + bj * 128, o); } }
.LBB0_98:
	s_ashr_i32 s2, s59, 4
	s_mul_hi_i32 s3, s2, 0x6000
	s_mulk_i32 s2, 0x6000
	v_lshl_or_b32 v156, s60, 8, v164
	s_add_u32 s2, s54, s2
	s_addc_u32 s3, s55, s3
	v_ashrrev_i32_e32 v157, 31, v156
	v_lshl_add_u64 v[118:119], v[156:157], 2, s[2:3]
	v_mov_b32_e32 v122, v228
	v_mov_b32_e32 v123, v229
	v_mov_b32_e32 v124, v230
	v_mov_b32_e32 v125, v231
	v_mov_b32_e32 v126, v232
	v_mov_b32_e32 v127, v233
	v_mov_b32_e32 v128, v234
	v_mov_b32_e32 v129, v235
	v_mov_b32_e32 v114, v236
	v_mov_b32_e32 v115, v237
	v_mov_b32_e32 v116, v238
	v_mov_b32_e32 v117, v239
	v_mov_b32_e32 v118, v240
	v_mov_b32_e32 v119, v241
	v_mov_b32_e32 v120, v242
	v_mov_b32_e32 v121, v243
	v_lshl_add_u32 v160, s59, 8, v162
	v_ashrrev_i32_e32 v161, 31, v160
	v_lshlrev_b64 v[158:159], 12, v[160:161]
	v_lshl_add_u64 v[166:167], s[16:17], 0, v[158:159]
	v_lshlrev_b64 v[158:159], 1, v[156:157]
	v_lshl_add_u64 v[156:157], v[166:167], 0, v[158:159]
	s_mov_b64 s[2:3], 0x80000
	s_mov_b64 s[24:25], -1
	s_waitcnt lgkmcnt(0)
	v_mul_f32_e32 v142, v142, v122
	v_mul_f32_e32 v161, v138, v126
	v_mul_f32_e32 v138, v143, v123
	v_mul_f32_e32 v143, v139, v127
	v_mul_f32_e32 v139, v144, v124
	v_mul_f32_e32 v144, v140, v128
	v_mul_f32_e32 v140, v145, v125
	v_mul_f32_e32 v141, v141, v129
	v_cvt_pk_bf16_f32 v138, v142, v138
	v_cvt_pk_bf16_f32 v139, v139, v140
	v_cvt_pk_bf16_f32 v140, v161, v143
	v_cvt_pk_bf16_f32 v141, v144, v141
	global_store_dwordx4 v[156:157], v[138:141], off
	v_mul_f32_e32 v134, v134, v114
	v_mul_f32_e32 v133, v133, v121
	v_mul_f32_e32 v138, v130, v118
	v_mul_f32_e32 v130, v135, v115
	v_mul_f32_e32 v135, v131, v119
	v_mul_f32_e32 v131, v136, v116
	v_mul_f32_e32 v136, v132, v120
	v_mul_f32_e32 v132, v137, v117
	v_cvt_pk_bf16_f32 v130, v134, v130
	v_cvt_pk_bf16_f32 v131, v131, v132
	v_cvt_pk_bf16_f32 v132, v138, v135
	v_cvt_pk_bf16_f32 v133, v136, v133
	global_store_dwordx4 v[156:157], v[130:133], off offset:256
	v_mul_f32_e32 v110, v110, v122
	v_mul_f32_e32 v109, v109, v129
	v_or_b32_e32 v130, 16, v160
	v_ashrrev_i32_e32 v131, 31, v130
	v_lshlrev_b64 v[130:131], 12, v[130:131]
	v_lshl_add_u64 v[130:131], s[16:17], 0, v[130:131]
	v_mul_f32_e32 v132, v106, v126
	v_mul_f32_e32 v106, v111, v123
	v_lshl_add_u64 v[130:131], v[130:131], 0, v[158:159]
	v_mul_f32_e32 v111, v107, v127
	v_mul_f32_e32 v107, v112, v124
	v_mul_f32_e32 v112, v108, v128
	v_mul_f32_e32 v108, v113, v125
	v_cvt_pk_bf16_f32 v106, v110, v106
	v_cvt_pk_bf16_f32 v107, v107, v108
	v_cvt_pk_bf16_f32 v108, v132, v111
	v_cvt_pk_bf16_f32 v109, v112, v109
	global_store_dwordx4 v[130:131], v[106:109], off
	v_mul_f32_e32 v102, v102, v114
	v_mul_f32_e32 v101, v101, v121
	v_mul_f32_e32 v106, v98, v118
	v_mul_f32_e32 v98, v103, v115
	v_mul_f32_e32 v103, v99, v119
	v_mul_f32_e32 v99, v104, v116
	v_mul_f32_e32 v104, v100, v120
	v_mul_f32_e32 v100, v105, v117
	v_cvt_pk_bf16_f32 v98, v102, v98
	v_cvt_pk_bf16_f32 v99, v99, v100
	v_cvt_pk_bf16_f32 v100, v106, v103
	v_cvt_pk_bf16_f32 v101, v104, v101
	global_store_dwordx4 v[130:131], v[98:101], off offset:256
	v_mul_f32_e32 v94, v94, v122
	v_mul_f32_e32 v93, v93, v129
	v_or_b32_e32 v98, 32, v160
	v_ashrrev_i32_e32 v99, 31, v98
	v_lshlrev_b64 v[98:99], 12, v[98:99]
	v_lshl_add_u64 v[98:99], s[16:17], 0, v[98:99]
	v_mul_f32_e32 v100, v90, v126
	v_mul_f32_e32 v90, v95, v123
	v_lshl_add_u64 v[98:99], v[98:99], 0, v[158:159]
	v_mul_f32_e32 v95, v91, v127
	v_mul_f32_e32 v91, v96, v124
	v_mul_f32_e32 v96, v92, v128
	v_mul_f32_e32 v92, v97, v125
	v_cvt_pk_bf16_f32 v90, v94, v90
	v_cvt_pk_bf16_f32 v91, v91, v92
	v_cvt_pk_bf16_f32 v92, v100, v95
	v_cvt_pk_bf16_f32 v93, v96, v93
	global_store_dwordx4 v[98:99], v[90:93], off
	v_mul_f32_e32 v82, v82, v114
	v_mul_f32_e32 v77, v77, v121
	v_mul_f32_e32 v90, v74, v118
	v_mul_f32_e32 v74, v83, v115
	v_mul_f32_e32 v83, v75, v119
	v_mul_f32_e32 v75, v84, v116
	v_mul_f32_e32 v84, v76, v120
	v_mul_f32_e32 v76, v85, v117
	v_cvt_pk_bf16_f32 v74, v82, v74
	v_cvt_pk_bf16_f32 v75, v75, v76
	v_cvt_pk_bf16_f32 v76, v90, v83
	v_cvt_pk_bf16_f32 v77, v84, v77
	global_store_dwordx4 v[98:99], v[74:77], off offset:256
	v_mul_f32_e32 v81, v81, v129
	v_mul_f32_e32 v70, v70, v114
	v_or_b32_e32 v74, 48, v160
	v_ashrrev_i32_e32 v75, 31, v74
	v_lshlrev_b64 v[74:75], 12, v[74:75]
	v_lshl_add_u64 v[74:75], s[16:17], 0, v[74:75]
	v_lshl_add_u64 v[82:83], v[74:75], 0, v[158:159]
	v_mul_f32_e32 v74, v86, v122
	v_mul_f32_e32 v76, v78, v126
	v_mul_f32_e32 v75, v87, v123
	v_mul_f32_e32 v77, v79, v127
	v_cvt_pk_bf16_f32 v74, v74, v75
	v_mul_f32_e32 v78, v88, v124
	v_mul_f32_e32 v79, v80, v128
	v_mul_f32_e32 v80, v89, v125
	v_cvt_pk_bf16_f32 v75, v78, v80
	v_cvt_pk_bf16_f32 v76, v76, v77
	v_cvt_pk_bf16_f32 v77, v79, v81
; #define PG8_BAR __builtin_amdgcn_s_barrier()
; __device__ __forceinline__ void st8(bf16_t* p, const float (&v)[8]) { u32x4 w; w.x = pk2(v[0], v[1]); w.y = pk2(v[2], v[3]); w.z = pk2(v[4], v[5]); w.w = pk2(v[6], v[7]); *(u32x4*)p = w; }
; template <class Epi, class Sched, bool ALIGN_EPI = false, bool SP2 = false>
; __device__ __forceinline__ void gemm_phase(PG8_LAS unsigned char* lds, const Gemm g, const Sched& S, const Epi& E) {
;     ...
;         if (!has_next) break;
; #pragma unroll
;         for (int a = 0; a < 2; ++a)
; #pragma unroll
;             for (int b = 0; b < 2; ++b)
; #pragma unroll
;                 for (int m = 0; m < 4; ++m)
; #pragma unroll
;                     for (int n = 0; n < 2; ++n) acc[a][b][m][n] = (f32x4){0.f, 0.f, 0.f, 0.f};
;         cur = nxt; cA = nA; cB = nB; ++ui;
;         if constexpr (ALIGN_EPI) { if (wr == 1) PG8_BAR; }
;     __device__ __forceinline__ void operator()(const f32x4 (&acc)[2][2][4][2], const Unit& u, int wr, int wc, int fr, int fq) const {
;     ...
;             for (int m = 0; m < 4; ++m) { bf16_t* rp = dl + (size_t)(row0 + ai * 128 + m * 16) * DM + col0;
; #pragma unroll
;                 for (int bj = 0; bj < 2; ++bj) { float o[8];
; #pragma unroll
;                     for (int j = 0; j < 4; ++j) { o[j] = g[bj][0][j] * acc[ai][bj][m][0][j]; o[4 + j] = g[bj][1][j] * acc[ai][bj][m][1][j]; }
;                     st8(rp + bj * 128, o); } }
	global_store_dwordx4 v[82:83], v[74:77], off
	v_mul_f32_e32 v69, v69, v121
	v_mul_f32_e32 v62, v62, v122
	v_mul_f32_e32 v74, v66, v118
	v_mul_f32_e32 v66, v71, v115
	v_mul_f32_e32 v71, v67, v119
	v_mul_f32_e32 v67, v72, v116
	v_mul_f32_e32 v72, v68, v120
	v_mul_f32_e32 v68, v73, v117
	v_cvt_pk_bf16_f32 v66, v70, v66
	v_cvt_pk_bf16_f32 v67, v67, v68
	v_cvt_pk_bf16_f32 v68, v74, v71
	v_cvt_pk_bf16_f32 v69, v72, v69
	global_store_dwordx4 v[82:83], v[66:69], off offset:256
	v_mul_f32_e32 v61, v61, v129
	v_mul_f32_e32 v46, v46, v114
	v_lshl_add_u64 v[66:67], v[156:157], 0, s[2:3]
	v_mul_f32_e32 v68, v58, v126
	v_mul_f32_e32 v58, v63, v123
	s_mov_b32 s2, 0x80000
	v_mul_f32_e32 v63, v59, v127
	v_mul_f32_e32 v59, v64, v124
	v_mul_f32_e32 v64, v60, v128
	v_mul_f32_e32 v60, v65, v125
	v_cvt_pk_bf16_f32 v58, v62, v58
	v_add_co_u32_e32 v62, vcc, s2, v156
	v_cvt_pk_bf16_f32 v59, v59, v60
	v_cvt_pk_bf16_f32 v60, v68, v63
	v_cvt_pk_bf16_f32 v61, v64, v61
	v_mul_f32_e32 v45, v45, v121
	s_nop 0
	v_addc_co_u32_e32 v63, vcc, 0, v157, vcc
	global_store_dwordx4 v[62:63], v[58:61], off
	s_mov_b64 s[2:3], 0x90000
	v_mul_f32_e32 v30, v30, v114
	v_mul_f32_e32 v58, v42, v118
	v_mul_f32_e32 v42, v47, v115
	v_mul_f32_e32 v47, v43, v119
	v_mul_f32_e32 v43, v48, v116
	v_mul_f32_e32 v48, v44, v120
	v_mul_f32_e32 v44, v49, v117
	v_cvt_pk_bf16_f32 v42, v46, v42
	v_cvt_pk_bf16_f32 v43, v43, v44
	v_cvt_pk_bf16_f32 v44, v58, v47
	v_cvt_pk_bf16_f32 v45, v48, v45
	global_store_dwordx4 v[66:67], v[42:45], off offset:256
	v_mul_f32_e32 v48, v56, v124
	v_mul_f32_e32 v49, v52, v128
	v_mul_f32_e32 v42, v54, v122
	v_mul_f32_e32 v43, v55, v123
	v_mul_f32_e32 v44, v50, v126
	v_mul_f32_e32 v45, v51, v127
	v_mul_f32_e32 v50, v57, v125
	v_cvt_pk_bf16_f32 v42, v42, v43
	v_cvt_pk_bf16_f32 v43, v48, v50
	v_add_co_u32_e32 v48, vcc, s76, v156
	v_mul_f32_e32 v51, v53, v129
	v_cvt_pk_bf16_f32 v44, v44, v45
	v_cvt_pk_bf16_f32 v45, v49, v51
	s_nop 0
	v_addc_co_u32_e32 v49, vcc, 0, v157, vcc
	global_store_dwordx4 v[48:49], v[42:45], off
	v_lshl_add_u64 v[46:47], v[156:157], 0, s[2:3]
	v_mul_f32_e32 v29, v29, v121
	v_mul_f32_e32 v42, v26, v118
	v_mul_f32_e32 v26, v31, v115
	v_mul_f32_e32 v31, v27, v119
	v_mul_f32_e32 v27, v32, v116
	v_mul_f32_e32 v32, v28, v120
	v_mul_f32_e32 v28, v33, v117
	v_cvt_pk_bf16_f32 v26, v30, v26
	v_cvt_pk_bf16_f32 v27, v27, v28
	s_mov_b64 s[2:3], 0xa0000
	v_cvt_pk_bf16_f32 v28, v42, v31
	v_cvt_pk_bf16_f32 v29, v32, v29
	global_store_dwordx4 v[46:47], v[26:29], off offset:256
	v_lshl_add_u64 v[30:31], v[156:157], 0, s[2:3]
	v_mul_f32_e32 v32, v40, v124
	v_mul_f32_e32 v26, v38, v122
	v_mul_f32_e32 v27, v39, v123
	s_mov_b32 s2, 0xa0000
	v_mul_f32_e32 v28, v34, v126
	v_mul_f32_e32 v29, v35, v127
	v_mul_f32_e32 v33, v36, v128
	v_mul_f32_e32 v34, v41, v125
	v_cvt_pk_bf16_f32 v26, v26, v27
	v_cvt_pk_bf16_f32 v27, v32, v34
	v_add_co_u32_e32 v32, vcc, s2, v156
	v_mul_f32_e32 v35, v37, v129
	v_cvt_pk_bf16_f32 v28, v28, v29
	v_cvt_pk_bf16_f32 v29, v33, v35
	s_nop 0
	v_addc_co_u32_e32 v33, vcc, 0, v157, vcc
	global_store_dwordx4 v[32:33], v[26:29], off
	v_mul_f32_e32 v14, v14, v114
	v_mul_f32_e32 v13, v13, v121
	v_mul_f32_e32 v26, v10, v118
	v_mul_f32_e32 v10, v15, v115
	v_mul_f32_e32 v15, v11, v119
	v_mul_f32_e32 v11, v16, v116
	v_mul_f32_e32 v16, v12, v120
	v_mul_f32_e32 v12, v17, v117
	v_cvt_pk_bf16_f32 v10, v14, v10
	v_cvt_pk_bf16_f32 v11, v11, v12
	s_mov_b64 s[2:3], 0xb0000
	v_cvt_pk_bf16_f32 v12, v26, v15
	v_cvt_pk_bf16_f32 v13, v16, v13
	global_store_dwordx4 v[30:31], v[10:13], off offset:256
	v_lshl_add_u64 v[14:15], v[156:157], 0, s[2:3]
	v_mul_f32_e32 v16, v24, v124
	v_mul_f32_e32 v10, v22, v122
	v_mul_f32_e32 v11, v23, v123
	s_mov_b32 s2, 0xb0000
	v_mul_f32_e32 v12, v18, v126
	v_mul_f32_e32 v13, v19, v127
	v_mul_f32_e32 v17, v20, v128
	v_mul_f32_e32 v18, v25, v125
	v_cvt_pk_bf16_f32 v10, v10, v11
	v_cvt_pk_bf16_f32 v11, v16, v18
	v_add_co_u32_e32 v16, vcc, s2, v156
	v_mul_f32_e32 v19, v21, v129
	v_cvt_pk_bf16_f32 v12, v12, v13
	v_cvt_pk_bf16_f32 v13, v17, v19
	s_nop 0
	v_addc_co_u32_e32 v17, vcc, 0, v157, vcc
	global_store_dwordx4 v[16:17], v[10:13], off
	v_mul_f32_e32 v5, v5, v121
	s_andn2_b64 vcc, exec, s[40:41]
	v_mul_f32_e32 v10, v2, v118
	v_mul_f32_e32 v2, v7, v115
	v_mul_f32_e32 v7, v3, v119
	v_mul_f32_e32 v3, v8, v116
	v_mul_f32_e32 v8, v4, v120
	v_mul_f32_e32 v4, v9, v117
	v_mul_f32_e32 v6, v6, v114
	v_cvt_pk_bf16_f32 v2, v6, v2
	v_cvt_pk_bf16_f32 v3, v3, v4
	v_cvt_pk_bf16_f32 v4, v10, v7
	v_cvt_pk_bf16_f32 v5, v8, v5
	global_store_dwordx4 v[14:15], v[2:5], off offset:256
	s_cbranch_vccnz .LBB0_87
	s_andn2_b64 vcc, exec, s[12:13]
	s_cbranch_vccnz .LBB0_86
	s_branch .LBB0_86

; #define PG8_STAGE(bufoff, gbase, voff) do { _Pragma("unroll") for (int _i = 0; _i < 2; ++_i) \
;         __builtin_amdgcn_global_load_lds((const unsigned*)((const char*)(gbase) + (voff)[_i]), (PG8_LAS unsigned*)(lds + (bufoff) + ldsw + _i * 8192), 16, 0, 0); } while (0)
; #define PG8_LDA(dst, b, h) do { _Pragma("unroll") for (int m = 0; m < 4; ++m) _Pragma("unroll") for (int k = 0; k < 2; ++k) dst[m][k] = *(const PG8_LAS bf16x8*)(lds + PG8_SA(b, h) + aoff + m * 2048 + k * 1024); } while (0)
; #define PG8_LDB(dst, b, h) do { _Pragma("unroll") for (int n = 0; n < 2; ++n) _Pragma("unroll") for (int k = 0; k < 2; ++k) dst[n][k] = *(const PG8_LAS bf16x8*)(lds + PG8_SB(b, h) + boff + n * 2048 + k * 1024); } while (0)
; #define PG8_MMA(ai, bj, At, Bt) do { __builtin_amdgcn_s_setprio(1); _Pragma("unroll") for (int m = 0; m < 4; ++m) _Pragma("unroll") for (int n = 0; n < 2; ++n) _Pragma("unroll") for (int k = 0; k < 2; ++k) \
;         acc[ai][bj][m][n] = __builtin_amdgcn_mfma_f32_16x16x32_bf16(Bt[n][k], At[m][k], acc[ai][bj][m][n], 0, 0, 0); __builtin_amdgcn_s_setprio(0); } while (0)
; #define PG8_WAIT_V(n) asm volatile("s_waitcnt vmcnt(" #n ")" ::: "memory")
; #define PG8_WAIT_L(n) asm volatile("s_waitcnt lgkmcnt(" #n ")" ::: "memory")
; #define PG8_BAR __builtin_amdgcn_s_barrier()
; #define PG8_SCHED __builtin_amdgcn_sched_barrier(0)
; template <class Epi, class Sched, bool ALIGN_EPI = false, bool SP2 = false>
; __device__ __forceinline__ void gemm_phase(PG8_LAS unsigned char* lds, const Gemm g, const Sched& S, const Epi& E) {
;     ...
;             PG8_LDB(B0, 0, 0); PG8_LDB(B1, 0, 1); PG8_SCHED; PG8_LDA(At, 0, 0); PG8_STAGE(PG8_SA(1, 1), a1 + hstep, voffA);
;             PG8_WAIT_V(8); PG8_WAIT_L(0); PG8_BAR; PG8_MMA(0, 0, At, B0); PG8_MMA(0, 1, At, B1); PG8_BAR; PG8_SCHED;
;             PG8_LDA(At, 0, 1); PG8_STAGE(PG8_SB(0, 0), b2, voffB); PG8_STAGE(PG8_SB(0, 1), b2 + hstep, voffB); PG8_STAGE(PG8_SA(0, 0), a2, voffA);
;             PG8_WAIT_V(8); PG8_WAIT_L(0); PG8_BAR; PG8_MMA(1, 0, At, B0); PG8_MMA(1, 1, At, B1); PG8_BAR; PG8_SCHED;
.LBB0_309:
	s_add_u32 s2, s12, 0xfff80080
	s_addc_u32 s3, s13, -1
	s_add_i32 s20, 0, 0x10000
	s_cmp_eq_u32 s53, 28
	s_cselect_b32 s27, s5, s3
	s_cselect_b32 s26, s6, s2
	v_add_u32_e32 v0, s20, v151
	v_add_u32_e32 v250, s20, v249
	s_cselect_b32 s25, s7, s30
	s_cselect_b32 s24, s8, s9
	s_add_i32 s33, 0, 0x14000
	ds_read_b128 v[142:145], v0
	s_waitcnt lgkmcnt(0)
	ds_read_b128 v[146:149], v250
	ds_read_b128 v[154:157], v0 offset:2048
	ds_read_b128 v[158:161], v250 offset:2048
	v_add_u32_e32 v0, s33, v151
	v_add_u32_e32 v251, s33, v249
	ds_read_b128 v[162:165], v0
	ds_read_b128 v[166:169], v251
	ds_read_b128 v[170:173], v0 offset:2048
	ds_read_b128 v[174:177], v251 offset:2048
	s_add_i32 m0, s65, 0xc000
	ds_read_b128 v[186:189], v153
	ds_read_b128 v[190:193], v248
	ds_read_b128 v[194:197], v153 offset:2048
	ds_read_b128 v[198:201], v248 offset:2048
	ds_read_b128 v[202:205], v153 offset:4096
	ds_read_b128 v[206:209], v248 offset:4096
	ds_read_b128 v[210:213], v153 offset:6144
	ds_read_b128 v[214:217], v248 offset:6144
	global_load_lds_dwordx4 v140, s[12:13]
	s_add_i32 m0, s65, 0xe000
	s_nop 0
	global_load_lds_dwordx4 v138, s[12:13]
	s_waitcnt vmcnt(8)
	s_waitcnt lgkmcnt(0)
	s_barrier
	s_setprio 1
	s_waitcnt lgkmcnt(0)
	v_mfma_f32_16x16x32_bf16 v[126:129], v[142:145], v[186:189], v[126:129]
	v_mfma_f32_16x16x32_bf16 v[122:125], v[154:157], v[186:189], v[122:125]
	v_mfma_f32_16x16x32_bf16 v[110:113], v[142:145], v[194:197], v[110:113]
	v_mfma_f32_16x16x32_bf16 v[106:109], v[154:157], v[194:197], v[106:109]
	v_mfma_f32_16x16x32_bf16 v[94:97], v[142:145], v[202:205], v[94:97]
	v_mfma_f32_16x16x32_bf16 v[90:93], v[154:157], v[202:205], v[90:93]
	v_mfma_f32_16x16x32_bf16 v[78:81], v[142:145], v[210:213], v[78:81]
	v_mfma_f32_16x16x32_bf16 v[74:77], v[154:157], v[210:213], v[74:77]
	v_mfma_f32_16x16x32_bf16 v[126:129], v[146:149], v[190:193], v[126:129]
	v_mfma_f32_16x16x32_bf16 v[122:125], v[158:161], v[190:193], v[122:125]
	v_mfma_f32_16x16x32_bf16 v[110:113], v[146:149], v[198:201], v[110:113]
	v_mfma_f32_16x16x32_bf16 v[106:109], v[158:161], v[198:201], v[106:109]
	v_mfma_f32_16x16x32_bf16 v[94:97], v[146:149], v[206:209], v[94:97]
	v_mfma_f32_16x16x32_bf16 v[90:93], v[158:161], v[206:209], v[90:93]
	v_mfma_f32_16x16x32_bf16 v[78:81], v[146:149], v[214:217], v[78:81]
	v_mfma_f32_16x16x32_bf16 v[74:77], v[158:161], v[214:217], v[74:77]
	s_setprio 0
	s_setprio 1
	v_mfma_f32_16x16x32_bf16 v[118:121], v[162:165], v[186:189], v[118:121]
	v_mfma_f32_16x16x32_bf16 v[114:117], v[170:173], v[186:189], v[114:117]
	v_mfma_f32_16x16x32_bf16 v[102:105], v[162:165], v[194:197], v[102:105]
	v_mfma_f32_16x16x32_bf16 v[98:101], v[170:173], v[194:197], v[98:101]
	v_mfma_f32_16x16x32_bf16 v[86:89], v[162:165], v[202:205], v[86:89]
	v_mfma_f32_16x16x32_bf16 v[82:85], v[170:173], v[202:205], v[82:85]
	v_mfma_f32_16x16x32_bf16 v[70:73], v[162:165], v[210:213], v[70:73]
	v_mfma_f32_16x16x32_bf16 v[66:69], v[170:173], v[210:213], v[66:69]
	v_mfma_f32_16x16x32_bf16 v[118:121], v[166:169], v[190:193], v[118:121]
	v_mfma_f32_16x16x32_bf16 v[114:117], v[174:177], v[190:193], v[114:117]
	v_mfma_f32_16x16x32_bf16 v[102:105], v[166:169], v[198:201], v[102:105]
	v_mfma_f32_16x16x32_bf16 v[98:101], v[174:177], v[198:201], v[98:101]
	v_mfma_f32_16x16x32_bf16 v[86:89], v[166:169], v[206:209], v[86:89]
	v_mfma_f32_16x16x32_bf16 v[82:85], v[174:177], v[206:209], v[82:85]
	v_mfma_f32_16x16x32_bf16 v[70:73], v[166:169], v[214:217], v[70:73]
	v_mfma_f32_16x16x32_bf16 v[66:69], v[174:177], v[214:217], v[66:69]
	s_setprio 0
	s_barrier
	s_add_i32 s2, s20, s64
	s_mov_b32 m0, s2
	ds_read_b128 v[186:189], v153 offset:16384
	ds_read_b128 v[190:193], v248 offset:16384
	ds_read_b128 v[194:197], v153 offset:18432
	ds_read_b128 v[198:201], v248 offset:18432
	ds_read_b128 v[202:205], v153 offset:20480
	ds_read_b128 v[206:209], v248 offset:20480
	ds_read_b128 v[210:213], v153 offset:22528
	ds_read_b128 v[214:217], v248 offset:22528
	global_load_lds_dwordx4 v134, s[24:25]
	s_add_i32 m0, s2, 0x2000
	s_add_u32 s2, s24, 0x80000
	s_addc_u32 s3, s25, 0
	s_add_i32 s20, s33, s64
	global_load_lds_dwordx4 v130, s[24:25]
	s_mov_b32 m0, s20
	s_nop 0
	global_load_lds_dwordx4 v134, s[2:3]
	s_add_i32 m0, s20, 0x2000
	s_nop 0
	global_load_lds_dwordx4 v130, s[2:3]
	s_mov_b32 m0, s65
	s_nop 0
	global_load_lds_dwordx4 v136, s[26:27]
	s_mov_b32 m0, s66
	s_nop 0
	global_load_lds_dwordx4 v132, s[26:27]
	s_waitcnt vmcnt(8)
	s_waitcnt lgkmcnt(0)
	s_barrier
	s_setprio 1
	s_waitcnt lgkmcnt(0)
	v_mfma_f32_16x16x32_bf16 v[62:65], v[142:145], v[186:189], v[62:65]
	v_mfma_f32_16x16x32_bf16 v[58:61], v[154:157], v[186:189], v[58:61]
	v_mfma_f32_16x16x32_bf16 v[46:49], v[142:145], v[194:197], v[46:49]
	v_mfma_f32_16x16x32_bf16 v[42:45], v[154:157], v[194:197], v[42:45]
	v_mfma_f32_16x16x32_bf16 v[30:33], v[142:145], v[202:205], v[30:33]
	v_mfma_f32_16x16x32_bf16 v[26:29], v[154:157], v[202:205], v[26:29]
	v_mfma_f32_16x16x32_bf16 v[14:17], v[142:145], v[210:213], v[14:17]
	v_mfma_f32_16x16x32_bf16 v[10:13], v[154:157], v[210:213], v[10:13]
	v_mfma_f32_16x16x32_bf16 v[62:65], v[146:149], v[190:193], v[62:65]
	v_mfma_f32_16x16x32_bf16 v[58:61], v[158:161], v[190:193], v[58:61]
	v_mfma_f32_16x16x32_bf16 v[46:49], v[146:149], v[198:201], v[46:49]
	v_mfma_f32_16x16x32_bf16 v[42:45], v[158:161], v[198:201], v[42:45]
	v_mfma_f32_16x16x32_bf16 v[30:33], v[146:149], v[206:209], v[30:33]
	v_mfma_f32_16x16x32_bf16 v[26:29], v[158:161], v[206:209], v[26:29]
	v_mfma_f32_16x16x32_bf16 v[14:17], v[146:149], v[214:217], v[14:17]
	v_mfma_f32_16x16x32_bf16 v[10:13], v[158:161], v[214:217], v[10:13]
	s_setprio 0
	s_setprio 1
	v_mfma_f32_16x16x32_bf16 v[54:57], v[162:165], v[186:189], v[54:57]
	v_mfma_f32_16x16x32_bf16 v[50:53], v[170:173], v[186:189], v[50:53]
	v_mfma_f32_16x16x32_bf16 v[38:41], v[162:165], v[194:197], v[38:41]
	v_mfma_f32_16x16x32_bf16 v[34:37], v[170:173], v[194:197], v[34:37]
	v_mfma_f32_16x16x32_bf16 v[22:25], v[162:165], v[202:205], v[22:25]
	v_mfma_f32_16x16x32_bf16 v[18:21], v[170:173], v[202:205], v[18:21]
	v_mfma_f32_16x16x32_bf16 v[6:9], v[162:165], v[210:213], v[6:9]
	v_mfma_f32_16x16x32_bf16 v[2:5], v[170:173], v[210:213], v[2:5]
	v_mfma_f32_16x16x32_bf16 v[54:57], v[166:169], v[190:193], v[54:57]
	v_mfma_f32_16x16x32_bf16 v[50:53], v[174:177], v[190:193], v[50:53]
	v_mfma_f32_16x16x32_bf16 v[38:41], v[166:169], v[198:201], v[38:41]
	v_mfma_f32_16x16x32_bf16 v[34:37], v[174:177], v[198:201], v[34:37]
	v_mfma_f32_16x16x32_bf16 v[22:25], v[166:169], v[206:209], v[22:25]
	v_mfma_f32_16x16x32_bf16 v[18:21], v[174:177], v[206:209], v[18:21]
	v_mfma_f32_16x16x32_bf16 v[6:9], v[166:169], v[214:217], v[6:9]
	v_mfma_f32_16x16x32_bf16 v[2:5], v[174:177], v[214:217], v[2:5]
	s_setprio 0
	s_barrier
; #define PG8_STAGE(bufoff, gbase, voff) do { _Pragma("unroll") for (int _i = 0; _i < 2; ++_i) \
;         __builtin_amdgcn_global_load_lds((const unsigned*)((const char*)(gbase) + (voff)[_i]), (PG8_LAS unsigned*)(lds + (bufoff) + ldsw + _i * 8192), 16, 0, 0); } while (0)
; #define PG8_LDA(dst, b, h) do { _Pragma("unroll") for (int m = 0; m < 4; ++m) _Pragma("unroll") for (int k = 0; k < 2; ++k) dst[m][k] = *(const PG8_LAS bf16x8*)(lds + PG8_SA(b, h) + aoff + m * 2048 + k * 1024); } while (0)
; #define PG8_LDB(dst, b, h) do { _Pragma("unroll") for (int n = 0; n < 2; ++n) _Pragma("unroll") for (int k = 0; k < 2; ++k) dst[n][k] = *(const PG8_LAS bf16x8*)(lds + PG8_SB(b, h) + boff + n * 2048 + k * 1024); } while (0)
; #define PG8_MMA(ai, bj, At, Bt) do { __builtin_amdgcn_s_setprio(1); _Pragma("unroll") for (int m = 0; m < 4; ++m) _Pragma("unroll") for (int n = 0; n < 2; ++n) _Pragma("unroll") for (int k = 0; k < 2; ++k) \
;         acc[ai][bj][m][n] = __builtin_amdgcn_mfma_f32_16x16x32_bf16(Bt[n][k], At[m][k], acc[ai][bj][m][n], 0, 0, 0); __builtin_amdgcn_s_setprio(0); } while (0)
; #define PG8_WAIT_V(n) asm volatile("s_waitcnt vmcnt(" #n ")" ::: "memory")
; #define PG8_WAIT_L(n) asm volatile("s_waitcnt lgkmcnt(" #n ")" ::: "memory")
; #define PG8_BAR __builtin_amdgcn_s_barrier()
; #define PG8_SCHED __builtin_amdgcn_sched_barrier(0)
; template <class Epi, class Sched, bool ALIGN_EPI = false, bool SP2 = false>
; __device__ __forceinline__ void gemm_phase(PG8_LAS unsigned char* lds, const Gemm g, const Sched& S, const Epi& E) {
;     ...
;             PG8_LDB(B0, 1, 0); PG8_LDB(B1, 1, 1); PG8_SCHED; PG8_LDA(At, 1, 0); PG8_STAGE(PG8_SA(0, 1), a2 + hstep, voffA);
;             PG8_WAIT_V(8); PG8_WAIT_L(0); PG8_BAR; PG8_MMA(0, 0, At, B0); PG8_MMA(0, 1, At, B1); PG8_BAR; PG8_SCHED;
;             PG8_LDA(At, 1, 1); PG8_STAGE(PG8_SB(1, 0), b3, voffB); PG8_STAGE(PG8_SB(1, 1), b3 + hstep, voffB); PG8_STAGE(PG8_SA(1, 0), a3, voffA);
;             PG8_WAIT_V(8); PG8_WAIT_L(0); PG8_BAR; PG8_MMA(1, 0, At, B0); PG8_MMA(1, 1, At, B1); PG8_BAR; PG8_SCHED;
;     ...
;         if constexpr (ALIGN_EPI) { if (wr == 0) PG8_BAR; }
	s_add_i32 s20, 0, 0x18000
	v_add_u32_e32 v0, s20, v151
	v_add_u32_e32 v250, s20, v249
	s_add_i32 s33, 0, 0x1c000
	ds_read_b128 v[142:145], v0
	ds_read_b128 v[146:149], v250
	ds_read_b128 v[154:157], v0 offset:2048
	ds_read_b128 v[158:161], v250 offset:2048
	v_add_u32_e32 v0, s33, v151
	v_add_u32_e32 v251, s33, v249
	ds_read_b128 v[162:165], v0
	ds_read_b128 v[166:169], v251
	ds_read_b128 v[170:173], v0 offset:2048
	ds_read_b128 v[174:177], v251 offset:2048
	s_add_u32 s2, s26, 0x80000
	s_addc_u32 s3, s27, 0
	s_mov_b32 m0, s67
	ds_read_b128 v[186:189], v153 offset:32768
	ds_read_b128 v[190:193], v248 offset:32768
	ds_read_b128 v[194:197], v153 offset:34816
	ds_read_b128 v[198:201], v248 offset:34816
	ds_read_b128 v[202:205], v153 offset:36864
	ds_read_b128 v[206:209], v248 offset:36864
	ds_read_b128 v[210:213], v153 offset:38912
	ds_read_b128 v[214:217], v248 offset:38912
	global_load_lds_dwordx4 v136, s[2:3]
	s_mov_b32 m0, s72
	s_nop 0
	global_load_lds_dwordx4 v132, s[2:3]
	s_waitcnt vmcnt(8)
	s_waitcnt lgkmcnt(0)
	s_barrier
	s_setprio 1
	s_waitcnt lgkmcnt(0)
	v_mfma_f32_16x16x32_bf16 v[126:129], v[142:145], v[186:189], v[126:129]
	v_mfma_f32_16x16x32_bf16 v[122:125], v[154:157], v[186:189], v[122:125]
	v_mfma_f32_16x16x32_bf16 v[110:113], v[142:145], v[194:197], v[110:113]
	v_mfma_f32_16x16x32_bf16 v[106:109], v[154:157], v[194:197], v[106:109]
	v_mfma_f32_16x16x32_bf16 v[94:97], v[142:145], v[202:205], v[94:97]
	v_mfma_f32_16x16x32_bf16 v[90:93], v[154:157], v[202:205], v[90:93]
	v_mfma_f32_16x16x32_bf16 v[78:81], v[142:145], v[210:213], v[78:81]
	v_mfma_f32_16x16x32_bf16 v[74:77], v[154:157], v[210:213], v[74:77]
	v_mfma_f32_16x16x32_bf16 v[126:129], v[146:149], v[190:193], v[126:129]
	v_mfma_f32_16x16x32_bf16 v[122:125], v[158:161], v[190:193], v[122:125]
	v_mfma_f32_16x16x32_bf16 v[110:113], v[146:149], v[198:201], v[110:113]
	v_mfma_f32_16x16x32_bf16 v[106:109], v[158:161], v[198:201], v[106:109]
	v_mfma_f32_16x16x32_bf16 v[94:97], v[146:149], v[206:209], v[94:97]
	v_mfma_f32_16x16x32_bf16 v[90:93], v[158:161], v[206:209], v[90:93]
	v_mfma_f32_16x16x32_bf16 v[78:81], v[146:149], v[214:217], v[78:81]
	v_mfma_f32_16x16x32_bf16 v[74:77], v[158:161], v[214:217], v[74:77]
	s_setprio 0
	s_setprio 1
	v_mfma_f32_16x16x32_bf16 v[118:121], v[162:165], v[186:189], v[118:121]
	v_mfma_f32_16x16x32_bf16 v[114:117], v[170:173], v[186:189], v[114:117]
	v_mfma_f32_16x16x32_bf16 v[102:105], v[162:165], v[194:197], v[102:105]
	v_mfma_f32_16x16x32_bf16 v[98:101], v[170:173], v[194:197], v[98:101]
	v_mfma_f32_16x16x32_bf16 v[86:89], v[162:165], v[202:205], v[86:89]
	v_mfma_f32_16x16x32_bf16 v[82:85], v[170:173], v[202:205], v[82:85]
	v_mfma_f32_16x16x32_bf16 v[70:73], v[162:165], v[210:213], v[70:73]
	v_mfma_f32_16x16x32_bf16 v[66:69], v[170:173], v[210:213], v[66:69]
	v_mfma_f32_16x16x32_bf16 v[118:121], v[166:169], v[190:193], v[118:121]
	v_mfma_f32_16x16x32_bf16 v[114:117], v[174:177], v[190:193], v[114:117]
	v_mfma_f32_16x16x32_bf16 v[102:105], v[166:169], v[198:201], v[102:105]
	v_mfma_f32_16x16x32_bf16 v[98:101], v[174:177], v[198:201], v[98:101]
	v_mfma_f32_16x16x32_bf16 v[86:89], v[166:169], v[206:209], v[86:89]
	v_mfma_f32_16x16x32_bf16 v[82:85], v[174:177], v[206:209], v[82:85]
	v_mfma_f32_16x16x32_bf16 v[70:73], v[166:169], v[214:217], v[70:73]
	v_mfma_f32_16x16x32_bf16 v[66:69], v[174:177], v[214:217], v[66:69]
	s_setprio 0
	s_barrier
	s_add_i32 s2, s20, s64
	s_add_i32 m0, s2, 0xffffff80
	ds_read_b128 v[186:189], v153 offset:49152
	ds_read_b128 v[190:193], v248 offset:49152
	ds_read_b128 v[194:197], v153 offset:51200
	ds_read_b128 v[198:201], v248 offset:51200
	ds_read_b128 v[202:205], v153 offset:53248
	ds_read_b128 v[206:209], v248 offset:53248
	ds_read_b128 v[210:213], v153 offset:55296
	ds_read_b128 v[214:217], v248 offset:55296
	global_load_lds_dwordx4 v134, s[24:25] offset:128
	s_add_i32 m0, s2, 0x1f80
	s_add_u32 s2, s24, 0x80080
	s_addc_u32 s3, s25, 0
	s_add_i32 s20, s33, s64
	global_load_lds_dwordx4 v130, s[24:25] offset:128
	s_mov_b32 m0, s20
	s_nop 0
	global_load_lds_dwordx4 v134, s[2:3]
	s_add_i32 m0, s20, 0x2000
	s_nop 0
	global_load_lds_dwordx4 v130, s[2:3]
	s_add_i32 m0, s86, 0xffffff80
	s_nop 0
	global_load_lds_dwordx4 v136, s[26:27] offset:128
	s_add_i32 m0, s87, 0xffffff80
	s_nop 0
	global_load_lds_dwordx4 v132, s[26:27] offset:128
	s_waitcnt vmcnt(8)
	s_waitcnt lgkmcnt(0)
	s_barrier
	s_setprio 1
	s_waitcnt lgkmcnt(0)
	v_mfma_f32_16x16x32_bf16 v[62:65], v[142:145], v[186:189], v[62:65]
	v_mfma_f32_16x16x32_bf16 v[58:61], v[154:157], v[186:189], v[58:61]
	v_mfma_f32_16x16x32_bf16 v[46:49], v[142:145], v[194:197], v[46:49]
	v_mfma_f32_16x16x32_bf16 v[42:45], v[154:157], v[194:197], v[42:45]
	v_mfma_f32_16x16x32_bf16 v[30:33], v[142:145], v[202:205], v[30:33]
	v_mfma_f32_16x16x32_bf16 v[26:29], v[154:157], v[202:205], v[26:29]
	v_mfma_f32_16x16x32_bf16 v[14:17], v[142:145], v[210:213], v[14:17]
	v_mfma_f32_16x16x32_bf16 v[10:13], v[154:157], v[210:213], v[10:13]
	v_mfma_f32_16x16x32_bf16 v[62:65], v[146:149], v[190:193], v[62:65]
	v_mfma_f32_16x16x32_bf16 v[58:61], v[158:161], v[190:193], v[58:61]
	v_mfma_f32_16x16x32_bf16 v[46:49], v[146:149], v[198:201], v[46:49]
	v_mfma_f32_16x16x32_bf16 v[42:45], v[158:161], v[198:201], v[42:45]
	v_mfma_f32_16x16x32_bf16 v[30:33], v[146:149], v[206:209], v[30:33]
	v_mfma_f32_16x16x32_bf16 v[26:29], v[158:161], v[206:209], v[26:29]
	v_mfma_f32_16x16x32_bf16 v[14:17], v[146:149], v[214:217], v[14:17]
	v_mfma_f32_16x16x32_bf16 v[10:13], v[158:161], v[214:217], v[10:13]
	s_setprio 0
	s_setprio 1
	v_mfma_f32_16x16x32_bf16 v[54:57], v[162:165], v[186:189], v[54:57]
	v_mfma_f32_16x16x32_bf16 v[50:53], v[170:173], v[186:189], v[50:53]
	v_mfma_f32_16x16x32_bf16 v[38:41], v[162:165], v[194:197], v[38:41]
	v_mfma_f32_16x16x32_bf16 v[34:37], v[170:173], v[194:197], v[34:37]
	v_mfma_f32_16x16x32_bf16 v[22:25], v[162:165], v[202:205], v[22:25]
	v_mfma_f32_16x16x32_bf16 v[18:21], v[170:173], v[202:205], v[18:21]
	v_mfma_f32_16x16x32_bf16 v[6:9], v[162:165], v[210:213], v[6:9]
	v_mfma_f32_16x16x32_bf16 v[2:5], v[170:173], v[210:213], v[2:5]
	v_mfma_f32_16x16x32_bf16 v[54:57], v[166:169], v[190:193], v[54:57]
	v_mfma_f32_16x16x32_bf16 v[50:53], v[174:177], v[190:193], v[50:53]
	v_mfma_f32_16x16x32_bf16 v[38:41], v[166:169], v[198:201], v[38:41]
	v_mfma_f32_16x16x32_bf16 v[34:37], v[174:177], v[198:201], v[34:37]
	v_mfma_f32_16x16x32_bf16 v[22:25], v[166:169], v[206:209], v[22:25]
	v_mfma_f32_16x16x32_bf16 v[18:21], v[174:177], v[206:209], v[18:21]
	v_mfma_f32_16x16x32_bf16 v[6:9], v[166:169], v[214:217], v[6:9]
	v_mfma_f32_16x16x32_bf16 v[2:5], v[174:177], v[214:217], v[2:5]
	s_setprio 0
	s_barrier
	s_add_i32 s53, s53, 2
	s_add_u32 s9, s9, 0x100
	s_addc_u32 s30, s30, 0
	s_add_u32 s12, s12, 0x100
	s_addc_u32 s13, s13, 0
	s_cmp_gt_u32 s53, 29
	s_cbranch_scc0 .LBB0_309
	s_and_b64 vcc, exec, s[50:51]
	s_cbranch_vccz .LBB0_312
	s_and_b64 vcc, exec, s[42:43]
	s_cbranch_vccnz .LBB0_312
	s_barrier

; #define PG8_BAR __builtin_amdgcn_s_barrier()
; template <class Epi, class Sched, bool ALIGN_EPI = false, bool SP2 = false>
; __device__ __forceinline__ void gemm_phase(PG8_LAS unsigned char* lds, const Gemm g, const Sched& S, const Epi& E) {
;     ...
;         if (!has_next) break;
; #pragma unroll
;         for (int a = 0; a < 2; ++a)
; #pragma unroll
;             for (int b = 0; b < 2; ++b)
; #pragma unroll
;                 for (int m = 0; m < 4; ++m)
; #pragma unroll
;                     for (int n = 0; n < 2; ++n) acc[a][b][m][n] = (f32x4){0.f, 0.f, 0.f, 0.f};
;         cur = nxt; cA = nA; cB = nB; ++ui;
;         if constexpr (ALIGN_EPI) { if (wr == 1) PG8_BAR; }
.LBB0_333:
	s_andn2_b64 vcc, exec, s[16:17]
	s_cbranch_vccnz .LBB0_304
	s_branch .LBB0_304

; #define PG8_STAGE(bufoff, gbase, voff) do { _Pragma("unroll") for (int _i = 0; _i < 2; ++_i) \
;         __builtin_amdgcn_global_load_lds((const unsigned*)((const char*)(gbase) + (voff)[_i]), (PG8_LAS unsigned*)(lds + (bufoff) + ldsw + _i * 8192), 16, 0, 0); } while (0)
; #define PG8_LDA(dst, b, h) do { _Pragma("unroll") for (int m = 0; m < 4; ++m) _Pragma("unroll") for (int k = 0; k < 2; ++k) dst[m][k] = *(const PG8_LAS bf16x8*)(lds + PG8_SA(b, h) + aoff + m * 2048 + k * 1024); } while (0)
; #define PG8_LDB(dst, b, h) do { _Pragma("unroll") for (int n = 0; n < 2; ++n) _Pragma("unroll") for (int k = 0; k < 2; ++k) dst[n][k] = *(const PG8_LAS bf16x8*)(lds + PG8_SB(b, h) + boff + n * 2048 + k * 1024); } while (0)
; #define PG8_MMA(ai, bj, At, Bt) do { __builtin_amdgcn_s_setprio(1); _Pragma("unroll") for (int m = 0; m < 4; ++m) _Pragma("unroll") for (int n = 0; n < 2; ++n) _Pragma("unroll") for (int k = 0; k < 2; ++k) \
;         acc[ai][bj][m][n] = __builtin_amdgcn_mfma_f32_16x16x32_bf16(Bt[n][k], At[m][k], acc[ai][bj][m][n], 0, 0, 0); __builtin_amdgcn_s_setprio(0); } while (0)
; #define PG8_WAIT_V(n) asm volatile("s_waitcnt vmcnt(" #n ")" ::: "memory")
; #define PG8_WAIT_L(n) asm volatile("s_waitcnt lgkmcnt(" #n ")" ::: "memory")
; #define PG8_BAR __builtin_amdgcn_s_barrier()
; #define PG8_SCHED __builtin_amdgcn_sched_barrier(0)
; template <class Epi, class Sched, bool ALIGN_EPI = false, bool SP2 = false>
; __device__ __forceinline__ void gemm_phase(PG8_LAS unsigned char* lds, const Gemm g, const Sched& S, const Epi& E) {
;     ...
;             PG8_LDB(B0, 0, 0); PG8_LDB(B1, 0, 1); PG8_SCHED; PG8_LDA(At, 0, 0); PG8_STAGE(PG8_SA(1, 1), a1 + hstep, voffA);
;             PG8_WAIT_V(8); PG8_WAIT_L(0); PG8_BAR; PG8_MMA(0, 0, At, B0); PG8_MMA(0, 1, At, B1); PG8_BAR; PG8_SCHED;
;             PG8_LDA(At, 0, 1); PG8_STAGE(PG8_SB(0, 0), b2, voffB); PG8_STAGE(PG8_SB(0, 1), b2 + hstep, voffB); PG8_STAGE(PG8_SA(0, 0), a2, voffA);
;             PG8_WAIT_V(8); PG8_WAIT_L(0); PG8_BAR; PG8_MMA(1, 0, At, B0); PG8_MMA(1, 1, At, B1); PG8_BAR; PG8_SCHED;
.LBB0_351:
	s_add_u32 s2, s12, 0xfff80080
	s_addc_u32 s3, s13, -1
	s_add_i32 s20, 0, 0x10000
	s_cmp_eq_u32 s51, 28
	s_cselect_b32 s43, s5, s3
	s_cselect_b32 s42, s6, s2
	v_add_u32_e32 v0, s20, v169
	v_add_u32_e32 v250, s20, v249
	s_cselect_b32 s25, s7, s49
	s_cselect_b32 s24, s8, s9
	s_add_i32 s33, 0, 0x14000
	ds_read_b128 v[2:5], v0
	ds_read_b128 v[6:9], v250
	ds_read_b128 v[138:141], v0 offset:2048
	ds_read_b128 v[142:145], v250 offset:2048
	v_add_u32_e32 v0, s33, v169
	v_add_u32_e32 v251, s33, v249
	ds_read_b128 v[164:167], v0
	ds_read_b128 v[174:177], v251
	ds_read_b128 v[186:189], v0 offset:2048
	ds_read_b128 v[190:193], v251 offset:2048
	s_add_i32 m0, s58, 0xc000
	ds_read_b128 v[194:197], v172
	ds_read_b128 v[198:201], v248
	ds_read_b128 v[202:205], v172 offset:2048
	ds_read_b128 v[206:209], v248 offset:2048
	ds_read_b128 v[210:213], v172 offset:4096
	ds_read_b128 v[214:217], v248 offset:4096
	ds_read_b128 v[218:221], v172 offset:6144
	ds_read_b128 v[222:225], v248 offset:6144
	global_load_lds_dwordx4 v160, s[12:13]
	s_add_i32 m0, s58, 0xe000
	s_nop 0
	global_load_lds_dwordx4 v158, s[12:13]
	s_waitcnt vmcnt(8)
	s_waitcnt lgkmcnt(0)
	s_barrier
	s_setprio 1
	s_waitcnt lgkmcnt(0)
	v_mfma_f32_16x16x32_bf16 v[134:137], v[2:5], v[194:197], v[134:137]
	v_mfma_f32_16x16x32_bf16 v[130:133], v[138:141], v[194:197], v[130:133]
	v_mfma_f32_16x16x32_bf16 v[118:121], v[2:5], v[202:205], v[118:121]
	v_mfma_f32_16x16x32_bf16 v[114:117], v[138:141], v[202:205], v[114:117]
	v_mfma_f32_16x16x32_bf16 v[102:105], v[2:5], v[210:213], v[102:105]
	v_mfma_f32_16x16x32_bf16 v[98:101], v[138:141], v[210:213], v[98:101]
	v_mfma_f32_16x16x32_bf16 v[86:89], v[2:5], v[218:221], v[86:89]
	v_mfma_f32_16x16x32_bf16 v[82:85], v[138:141], v[218:221], v[82:85]
	v_mfma_f32_16x16x32_bf16 v[134:137], v[6:9], v[198:201], v[134:137]
	v_mfma_f32_16x16x32_bf16 v[130:133], v[142:145], v[198:201], v[130:133]
	v_mfma_f32_16x16x32_bf16 v[118:121], v[6:9], v[206:209], v[118:121]
	v_mfma_f32_16x16x32_bf16 v[114:117], v[142:145], v[206:209], v[114:117]
	v_mfma_f32_16x16x32_bf16 v[102:105], v[6:9], v[214:217], v[102:105]
	v_mfma_f32_16x16x32_bf16 v[98:101], v[142:145], v[214:217], v[98:101]
	v_mfma_f32_16x16x32_bf16 v[86:89], v[6:9], v[222:225], v[86:89]
	v_mfma_f32_16x16x32_bf16 v[82:85], v[142:145], v[222:225], v[82:85]
	s_setprio 0
	s_setprio 1
	v_mfma_f32_16x16x32_bf16 v[126:129], v[164:167], v[194:197], v[126:129]
	v_mfma_f32_16x16x32_bf16 v[122:125], v[186:189], v[194:197], v[122:125]
	v_mfma_f32_16x16x32_bf16 v[110:113], v[164:167], v[202:205], v[110:113]
	v_mfma_f32_16x16x32_bf16 v[106:109], v[186:189], v[202:205], v[106:109]
	v_mfma_f32_16x16x32_bf16 v[94:97], v[164:167], v[210:213], v[94:97]
	v_mfma_f32_16x16x32_bf16 v[90:93], v[186:189], v[210:213], v[90:93]
	v_mfma_f32_16x16x32_bf16 v[78:81], v[164:167], v[218:221], v[78:81]
	v_mfma_f32_16x16x32_bf16 v[74:77], v[186:189], v[218:221], v[74:77]
	v_mfma_f32_16x16x32_bf16 v[126:129], v[174:177], v[198:201], v[126:129]
	v_mfma_f32_16x16x32_bf16 v[122:125], v[190:193], v[198:201], v[122:125]
	v_mfma_f32_16x16x32_bf16 v[110:113], v[174:177], v[206:209], v[110:113]
	v_mfma_f32_16x16x32_bf16 v[106:109], v[190:193], v[206:209], v[106:109]
	v_mfma_f32_16x16x32_bf16 v[94:97], v[174:177], v[214:217], v[94:97]
	v_mfma_f32_16x16x32_bf16 v[90:93], v[190:193], v[214:217], v[90:93]
	v_mfma_f32_16x16x32_bf16 v[78:81], v[174:177], v[222:225], v[78:81]
	v_mfma_f32_16x16x32_bf16 v[74:77], v[190:193], v[222:225], v[74:77]
	s_setprio 0
	s_barrier
	s_add_i32 s2, s20, s57
	s_mov_b32 m0, s2
	ds_read_b128 v[194:197], v172 offset:16384
	ds_read_b128 v[198:201], v248 offset:16384
	ds_read_b128 v[202:205], v172 offset:18432
	ds_read_b128 v[206:209], v248 offset:18432
	ds_read_b128 v[210:213], v172 offset:20480
	ds_read_b128 v[214:217], v248 offset:20480
	ds_read_b128 v[218:221], v172 offset:22528
	ds_read_b128 v[222:225], v248 offset:22528
	global_load_lds_dwordx4 v150, s[24:25]
	s_add_i32 m0, s2, 0x2000
	s_add_u32 s2, s24, 0x80000
	s_addc_u32 s3, s25, 0
	s_add_i32 s20, s33, s57
	global_load_lds_dwordx4 v146, s[24:25]
	s_mov_b32 m0, s20
	s_nop 0
	global_load_lds_dwordx4 v150, s[2:3]
	s_add_i32 m0, s20, 0x2000
	s_nop 0
	global_load_lds_dwordx4 v146, s[2:3]
	s_mov_b32 m0, s58
	s_nop 0
	global_load_lds_dwordx4 v152, s[42:43]
	s_mov_b32 m0, s59
	s_nop 0
	global_load_lds_dwordx4 v148, s[42:43]
	s_waitcnt vmcnt(8)
	s_waitcnt lgkmcnt(0)
	s_barrier
	s_setprio 1
	s_waitcnt lgkmcnt(0)
	v_mfma_f32_16x16x32_bf16 v[70:73], v[2:5], v[194:197], v[70:73]
	v_mfma_f32_16x16x32_bf16 v[66:69], v[138:141], v[194:197], v[66:69]
	v_mfma_f32_16x16x32_bf16 v[54:57], v[2:5], v[202:205], v[54:57]
	v_mfma_f32_16x16x32_bf16 v[50:53], v[138:141], v[202:205], v[50:53]
	v_mfma_f32_16x16x32_bf16 v[38:41], v[2:5], v[210:213], v[38:41]
	v_mfma_f32_16x16x32_bf16 v[34:37], v[138:141], v[210:213], v[34:37]
	v_mfma_f32_16x16x32_bf16 v[2:5], v[2:5], v[218:221], v[22:25]
	v_mfma_f32_16x16x32_bf16 v[70:73], v[6:9], v[198:201], v[70:73]
	v_mfma_f32_16x16x32_bf16 v[66:69], v[142:145], v[198:201], v[66:69]
	v_mfma_f32_16x16x32_bf16 v[54:57], v[6:9], v[206:209], v[54:57]
	v_mfma_f32_16x16x32_bf16 v[50:53], v[142:145], v[206:209], v[50:53]
	v_mfma_f32_16x16x32_bf16 v[38:41], v[6:9], v[214:217], v[38:41]
	v_mfma_f32_16x16x32_bf16 v[34:37], v[142:145], v[214:217], v[34:37]
	v_mfma_f32_16x16x32_bf16 v[2:5], v[6:9], v[222:225], v[2:5]
	v_mfma_f32_16x16x32_bf16 v[6:9], v[138:141], v[218:221], v[18:21]
	v_mfma_f32_16x16x32_bf16 v[6:9], v[142:145], v[222:225], v[6:9]
	s_setprio 0
	s_setprio 1
	v_mfma_f32_16x16x32_bf16 v[18:21], v[164:167], v[194:197], v[62:65]
	v_mfma_f32_16x16x32_bf16 v[62:65], v[174:177], v[198:201], v[18:21]
	v_mfma_f32_16x16x32_bf16 v[18:21], v[186:189], v[194:197], v[58:61]
	v_mfma_f32_16x16x32_bf16 v[58:61], v[190:193], v[198:201], v[18:21]
	v_mfma_f32_16x16x32_bf16 v[18:21], v[164:167], v[202:205], v[46:49]
	v_mfma_f32_16x16x32_bf16 v[46:49], v[174:177], v[206:209], v[18:21]
	v_mfma_f32_16x16x32_bf16 v[18:21], v[186:189], v[202:205], v[42:45]
	v_mfma_f32_16x16x32_bf16 v[42:45], v[190:193], v[206:209], v[18:21]
	v_mfma_f32_16x16x32_bf16 v[18:21], v[164:167], v[210:213], v[30:33]
	v_mfma_f32_16x16x32_bf16 v[30:33], v[174:177], v[214:217], v[18:21]
	v_mfma_f32_16x16x32_bf16 v[18:21], v[186:189], v[210:213], v[26:29]
	v_mfma_f32_16x16x32_bf16 v[14:17], v[164:167], v[218:221], v[14:17]
	v_mfma_f32_16x16x32_bf16 v[10:13], v[186:189], v[218:221], v[10:13]
	v_mfma_f32_16x16x32_bf16 v[26:29], v[190:193], v[214:217], v[18:21]
	v_mfma_f32_16x16x32_bf16 v[14:17], v[174:177], v[222:225], v[14:17]
	v_mfma_f32_16x16x32_bf16 v[10:13], v[190:193], v[222:225], v[10:13]
	s_setprio 0
	s_barrier
; #define PG8_STAGE(bufoff, gbase, voff) do { _Pragma("unroll") for (int _i = 0; _i < 2; ++_i) \
;         __builtin_amdgcn_global_load_lds((const unsigned*)((const char*)(gbase) + (voff)[_i]), (PG8_LAS unsigned*)(lds + (bufoff) + ldsw + _i * 8192), 16, 0, 0); } while (0)
; #define PG8_LDA(dst, b, h) do { _Pragma("unroll") for (int m = 0; m < 4; ++m) _Pragma("unroll") for (int k = 0; k < 2; ++k) dst[m][k] = *(const PG8_LAS bf16x8*)(lds + PG8_SA(b, h) + aoff + m * 2048 + k * 1024); } while (0)
; #define PG8_LDB(dst, b, h) do { _Pragma("unroll") for (int n = 0; n < 2; ++n) _Pragma("unroll") for (int k = 0; k < 2; ++k) dst[n][k] = *(const PG8_LAS bf16x8*)(lds + PG8_SB(b, h) + boff + n * 2048 + k * 1024); } while (0)
; #define PG8_MMA(ai, bj, At, Bt) do { __builtin_amdgcn_s_setprio(1); _Pragma("unroll") for (int m = 0; m < 4; ++m) _Pragma("unroll") for (int n = 0; n < 2; ++n) _Pragma("unroll") for (int k = 0; k < 2; ++k) \
;         acc[ai][bj][m][n] = __builtin_amdgcn_mfma_f32_16x16x32_bf16(Bt[n][k], At[m][k], acc[ai][bj][m][n], 0, 0, 0); __builtin_amdgcn_s_setprio(0); } while (0)
; #define PG8_WAIT_V(n) asm volatile("s_waitcnt vmcnt(" #n ")" ::: "memory")
; #define PG8_WAIT_L(n) asm volatile("s_waitcnt lgkmcnt(" #n ")" ::: "memory")
; #define PG8_BAR __builtin_amdgcn_s_barrier()
; #define PG8_SCHED __builtin_amdgcn_sched_barrier(0)
; template <class Epi, class Sched, bool ALIGN_EPI = false, bool SP2 = false>
; __device__ __forceinline__ void gemm_phase(PG8_LAS unsigned char* lds, const Gemm g, const Sched& S, const Epi& E) {
;     ...
;             PG8_LDB(B0, 1, 0); PG8_LDB(B1, 1, 1); PG8_SCHED; PG8_LDA(At, 1, 0); PG8_STAGE(PG8_SA(0, 1), a2 + hstep, voffA);
;             PG8_WAIT_V(8); PG8_WAIT_L(0); PG8_BAR; PG8_MMA(0, 0, At, B0); PG8_MMA(0, 1, At, B1); PG8_BAR; PG8_SCHED;
;             PG8_LDA(At, 1, 1); PG8_STAGE(PG8_SB(1, 0), b3, voffB); PG8_STAGE(PG8_SB(1, 1), b3 + hstep, voffB); PG8_STAGE(PG8_SA(1, 0), a3, voffA);
;             PG8_WAIT_V(8); PG8_WAIT_L(0); PG8_BAR; PG8_MMA(1, 0, At, B0); PG8_MMA(1, 1, At, B1); PG8_BAR; PG8_SCHED;
;     ...
;         if constexpr (ALIGN_EPI) { if (wr == 0) PG8_BAR; }
	s_add_i32 s20, 0, 0x18000
	v_add_u32_e32 v0, s20, v169
	v_add_u32_e32 v250, s20, v249
	s_add_i32 s33, 0, 0x1c000
	ds_read_b128 v[18:21], v0
	ds_read_b128 v[22:25], v250
	ds_read_b128 v[138:141], v0 offset:2048
	ds_read_b128 v[142:145], v250 offset:2048
	v_add_u32_e32 v0, s33, v169
	v_add_u32_e32 v251, s33, v249
	ds_read_b128 v[164:167], v0
	ds_read_b128 v[174:177], v251
	ds_read_b128 v[186:189], v0 offset:2048
	ds_read_b128 v[190:193], v251 offset:2048
	s_add_u32 s2, s42, 0x80000
	s_addc_u32 s3, s43, 0
	s_mov_b32 m0, s60
	ds_read_b128 v[194:197], v172 offset:32768
	ds_read_b128 v[198:201], v248 offset:32768
	ds_read_b128 v[202:205], v172 offset:34816
	ds_read_b128 v[206:209], v248 offset:34816
	ds_read_b128 v[210:213], v172 offset:36864
	ds_read_b128 v[214:217], v248 offset:36864
	ds_read_b128 v[218:221], v172 offset:38912
	ds_read_b128 v[222:225], v248 offset:38912
	global_load_lds_dwordx4 v152, s[2:3]
	s_mov_b32 m0, s61
	s_nop 0
	global_load_lds_dwordx4 v148, s[2:3]
	s_waitcnt vmcnt(8)
	s_waitcnt lgkmcnt(0)
	s_barrier
	s_setprio 1
	s_waitcnt lgkmcnt(0)
	v_mfma_f32_16x16x32_bf16 v[134:137], v[18:21], v[194:197], v[134:137]
	v_mfma_f32_16x16x32_bf16 v[130:133], v[138:141], v[194:197], v[130:133]
	v_mfma_f32_16x16x32_bf16 v[118:121], v[18:21], v[202:205], v[118:121]
	v_mfma_f32_16x16x32_bf16 v[114:117], v[138:141], v[202:205], v[114:117]
	v_mfma_f32_16x16x32_bf16 v[102:105], v[18:21], v[210:213], v[102:105]
	v_mfma_f32_16x16x32_bf16 v[98:101], v[138:141], v[210:213], v[98:101]
	v_mfma_f32_16x16x32_bf16 v[86:89], v[18:21], v[218:221], v[86:89]
	v_mfma_f32_16x16x32_bf16 v[82:85], v[138:141], v[218:221], v[82:85]
	v_mfma_f32_16x16x32_bf16 v[134:137], v[22:25], v[198:201], v[134:137]
	v_mfma_f32_16x16x32_bf16 v[130:133], v[142:145], v[198:201], v[130:133]
	v_mfma_f32_16x16x32_bf16 v[118:121], v[22:25], v[206:209], v[118:121]
	v_mfma_f32_16x16x32_bf16 v[114:117], v[142:145], v[206:209], v[114:117]
	v_mfma_f32_16x16x32_bf16 v[102:105], v[22:25], v[214:217], v[102:105]
	v_mfma_f32_16x16x32_bf16 v[98:101], v[142:145], v[214:217], v[98:101]
	v_mfma_f32_16x16x32_bf16 v[86:89], v[22:25], v[222:225], v[86:89]
	v_mfma_f32_16x16x32_bf16 v[82:85], v[142:145], v[222:225], v[82:85]
	s_setprio 0
	s_setprio 1
	v_mfma_f32_16x16x32_bf16 v[126:129], v[164:167], v[194:197], v[126:129]
	v_mfma_f32_16x16x32_bf16 v[122:125], v[186:189], v[194:197], v[122:125]
	v_mfma_f32_16x16x32_bf16 v[110:113], v[164:167], v[202:205], v[110:113]
	v_mfma_f32_16x16x32_bf16 v[106:109], v[186:189], v[202:205], v[106:109]
	v_mfma_f32_16x16x32_bf16 v[94:97], v[164:167], v[210:213], v[94:97]
	v_mfma_f32_16x16x32_bf16 v[90:93], v[186:189], v[210:213], v[90:93]
	v_mfma_f32_16x16x32_bf16 v[78:81], v[164:167], v[218:221], v[78:81]
	v_mfma_f32_16x16x32_bf16 v[74:77], v[186:189], v[218:221], v[74:77]
	v_mfma_f32_16x16x32_bf16 v[126:129], v[174:177], v[198:201], v[126:129]
	v_mfma_f32_16x16x32_bf16 v[122:125], v[190:193], v[198:201], v[122:125]
	v_mfma_f32_16x16x32_bf16 v[110:113], v[174:177], v[206:209], v[110:113]
	v_mfma_f32_16x16x32_bf16 v[106:109], v[190:193], v[206:209], v[106:109]
	v_mfma_f32_16x16x32_bf16 v[94:97], v[174:177], v[214:217], v[94:97]
	v_mfma_f32_16x16x32_bf16 v[90:93], v[190:193], v[214:217], v[90:93]
	v_mfma_f32_16x16x32_bf16 v[78:81], v[174:177], v[222:225], v[78:81]
	v_mfma_f32_16x16x32_bf16 v[74:77], v[190:193], v[222:225], v[74:77]
	s_setprio 0
	s_barrier
	s_add_i32 s2, s20, s57
	s_add_i32 m0, s2, 0xffffff80
	ds_read_b128 v[194:197], v172 offset:49152
	ds_read_b128 v[198:201], v248 offset:49152
	ds_read_b128 v[202:205], v172 offset:51200
	ds_read_b128 v[206:209], v248 offset:51200
	ds_read_b128 v[210:213], v172 offset:53248
	ds_read_b128 v[214:217], v248 offset:53248
	ds_read_b128 v[218:221], v172 offset:55296
	ds_read_b128 v[222:225], v248 offset:55296
	global_load_lds_dwordx4 v150, s[24:25] offset:128
	s_add_i32 m0, s2, 0x1f80
	s_add_u32 s2, s24, 0x80080
	s_addc_u32 s3, s25, 0
	s_add_i32 s20, s33, s57
	global_load_lds_dwordx4 v146, s[24:25] offset:128
	s_mov_b32 m0, s20
	s_nop 0
	global_load_lds_dwordx4 v150, s[2:3]
	s_add_i32 m0, s20, 0x2000
	s_nop 0
	global_load_lds_dwordx4 v146, s[2:3]
	s_add_i32 m0, s64, 0xffffff80
	s_nop 0
	global_load_lds_dwordx4 v152, s[42:43] offset:128
	s_add_i32 m0, s65, 0xffffff80
	s_nop 0
	global_load_lds_dwordx4 v148, s[42:43] offset:128
	s_waitcnt vmcnt(8)
	s_waitcnt lgkmcnt(0)
	s_barrier
	s_setprio 1
	s_waitcnt lgkmcnt(0)
	v_mfma_f32_16x16x32_bf16 v[70:73], v[18:21], v[194:197], v[70:73]
	v_mfma_f32_16x16x32_bf16 v[54:57], v[18:21], v[202:205], v[54:57]
	v_mfma_f32_16x16x32_bf16 v[38:41], v[18:21], v[210:213], v[38:41]
	v_mfma_f32_16x16x32_bf16 v[2:5], v[18:21], v[218:221], v[2:5]
	v_mfma_f32_16x16x32_bf16 v[70:73], v[22:25], v[198:201], v[70:73]
	v_mfma_f32_16x16x32_bf16 v[66:69], v[138:141], v[194:197], v[66:69]
	v_mfma_f32_16x16x32_bf16 v[54:57], v[22:25], v[206:209], v[54:57]
	v_mfma_f32_16x16x32_bf16 v[50:53], v[138:141], v[202:205], v[50:53]
	v_mfma_f32_16x16x32_bf16 v[38:41], v[22:25], v[214:217], v[38:41]
	v_mfma_f32_16x16x32_bf16 v[34:37], v[138:141], v[210:213], v[34:37]
	v_mfma_f32_16x16x32_bf16 v[22:25], v[22:25], v[222:225], v[2:5]
	v_mfma_f32_16x16x32_bf16 v[2:5], v[138:141], v[218:221], v[6:9]
	v_mfma_f32_16x16x32_bf16 v[66:69], v[142:145], v[198:201], v[66:69]
	v_mfma_f32_16x16x32_bf16 v[50:53], v[142:145], v[206:209], v[50:53]
	v_mfma_f32_16x16x32_bf16 v[34:37], v[142:145], v[214:217], v[34:37]
	v_mfma_f32_16x16x32_bf16 v[18:21], v[142:145], v[222:225], v[2:5]
	s_setprio 0
	s_setprio 1
	v_mfma_f32_16x16x32_bf16 v[2:5], v[164:167], v[194:197], v[62:65]
	v_mfma_f32_16x16x32_bf16 v[62:65], v[174:177], v[198:201], v[2:5]
	v_mfma_f32_16x16x32_bf16 v[2:5], v[186:189], v[194:197], v[58:61]
	v_mfma_f32_16x16x32_bf16 v[58:61], v[190:193], v[198:201], v[2:5]
	v_mfma_f32_16x16x32_bf16 v[2:5], v[164:167], v[202:205], v[46:49]
	v_mfma_f32_16x16x32_bf16 v[46:49], v[174:177], v[206:209], v[2:5]
	v_mfma_f32_16x16x32_bf16 v[2:5], v[186:189], v[202:205], v[42:45]
	v_mfma_f32_16x16x32_bf16 v[42:45], v[190:193], v[206:209], v[2:5]
	v_mfma_f32_16x16x32_bf16 v[2:5], v[164:167], v[210:213], v[30:33]
	v_mfma_f32_16x16x32_bf16 v[30:33], v[174:177], v[214:217], v[2:5]
	v_mfma_f32_16x16x32_bf16 v[2:5], v[186:189], v[210:213], v[26:29]
	v_mfma_f32_16x16x32_bf16 v[26:29], v[190:193], v[214:217], v[2:5]
	v_mfma_f32_16x16x32_bf16 v[2:5], v[164:167], v[218:221], v[14:17]
	v_mfma_f32_16x16x32_bf16 v[14:17], v[174:177], v[222:225], v[2:5]
	v_mfma_f32_16x16x32_bf16 v[2:5], v[186:189], v[218:221], v[10:13]
	v_mfma_f32_16x16x32_bf16 v[10:13], v[190:193], v[222:225], v[2:5]
	s_setprio 0
	s_barrier
	s_add_i32 s51, s51, 2
	s_add_u32 s9, s9, 0x100
	s_addc_u32 s49, s49, 0
	s_add_u32 s12, s12, 0x100
	s_addc_u32 s13, s13, 0
	s_cmp_gt_u32 s51, 29
	s_cbranch_scc0 .LBB0_351
	s_and_b64 vcc, exec, s[26:27]
	s_cbranch_vccz .LBB0_356
	s_and_b64 vcc, exec, s[40:41]
	s_cbranch_vccnz .Lstag3_skip
	s_barrier
.Lstag3_skip:
	v_lshl_add_u32 v164, s4, 8, v168
	s_cmp_gt_i32 s72, 7
	s_mov_b64 s[12:13], -1
	s_cbranch_scc1 .LBB0_357
